# attention items: bit-trick bf16 packs -> v_cvt_pk_bf16_f32 (42 pairs); plus HC pass-A load hoisting
# speedup vs baseline: 1.0259x; 1.0025x over previous
.LBB0_375:
	v_readlane_b32 s8, v253, 54
	v_readlane_b32 s9, v253, 55
	s_mov_b64 s[36:37], -1
	s_mov_b64 s[38:39], -1
	s_waitcnt lgkmcnt(0)
	s_nop 4
	global_load_dword v0, v16, s[8:9] sc1
	global_load_dword v1, v16, s[8:9] offset:256 sc1
	global_load_dword v2, v16, s[8:9] offset:512 sc1
	global_load_dword v3, v16, s[8:9] offset:768 sc1
	global_load_dword v4, v16, s[8:9] offset:1024 sc1
	global_load_dword v5, v16, s[8:9] offset:1280 sc1
	global_load_dword v6, v16, s[8:9] offset:1536 sc1
	global_load_dword v7, v16, s[8:9] offset:1792 sc1
	global_load_dword v8, v16, s[8:9] offset:2048 sc1
	global_load_dword v9, v16, s[8:9] offset:2304 sc1
	global_load_dword v10, v16, s[8:9] offset:2560 sc1
	global_load_dword v11, v16, s[8:9] offset:2816 sc1
	global_load_dword v12, v16, s[8:9] offset:3072 sc1
	global_load_dword v13, v16, s[8:9] offset:3328 sc1
	global_load_dword v14, v16, s[8:9] offset:3584 sc1
	global_load_dword v15, v16, s[8:9] offset:3840 sc1
	s_waitcnt vmcnt(0)
	v_add_u32_e32 v17, v1, v0
	v_add_u32_e32 v17, v17, v2
	v_add_u32_e32 v17, v17, v3
	v_add_u32_e32 v17, v17, v4
	v_add_u32_e32 v17, v17, v5
	v_add_u32_e32 v17, v17, v6
	v_add_u32_e32 v17, v17, v7
	v_add_u32_e32 v17, v17, v8
	v_add_u32_e32 v17, v17, v9
	v_add_u32_e32 v17, v17, v10
	v_add_u32_e32 v17, v17, v11
	v_add_u32_e32 v17, v17, v12
	v_add_u32_e32 v17, v17, v13
	v_add_u32_e32 v17, v17, v14
	v_add_u32_e32 v17, v17, v15
	v_cmp_eq_u32_e32 vcc, s83, v17
	s_cbranch_vccnz .LBB0_374
	s_and_b32 s1, s0, 0xff
	s_cmp_eq_u32 s1, 0
	s_mov_b64 s[40:41], -1
	s_sleep 1
	s_cbranch_scc1 .LBB0_379
	s_and_b64 vcc, exec, s[40:41]
	s_cbranch_vccz .LBB0_374

.LBB0_428:
	s_waitcnt vmcnt(7)
	v_add_f32_e32 v0, v33, v32
	v_add_f32_e32 v0, v34, v0
	v_add_f32_e32 v1, v37, v36
	v_add_f32_e32 v0, v35, v0
	v_add_f32_e32 v1, v38, v1
	v_add_f32_e32 v0, 0, v0
	v_add_f32_e32 v1, v39, v1
	v_add_f32_e32 v0, v1, v0
	v_add_f32_e32 v1, v41, v40
	v_add_f32_e32 v1, v42, v1
	v_add_f32_e32 v1, v43, v1
	v_add_f32_e32 v0, v1, v0
	v_add_f32_e32 v1, v45, v44
	v_add_f32_e32 v1, v46, v1
	v_add_f32_e32 v1, v47, v1
	s_waitcnt vmcnt(6)
	v_add_f32_e32 v4, v1, v0
	v_mov_b32_e32 v0, v57
	v_mov_b32_e32 v1, v49
	v_mov_b32_e32 v2, v56
	v_mov_b32_e32 v3, v48
	v_pk_add_f32 v[0:1], v[0:1], v[2:3]
	v_mov_b32_e32 v2, v58
	v_mov_b32_e32 v3, v50
	v_pk_add_f32 v[0:1], v[2:3], v[0:1]
	v_mov_b32_e32 v2, v59
	v_mov_b32_e32 v3, v51
	v_pk_add_f32 v[0:1], v[2:3], v[0:1]
	v_mov_b32_e32 v2, v60
	v_add_f32_e32 v1, v1, v4
	v_add_f32_e32 v4, v0, v1
	v_mov_b32_e32 v0, v61
	v_mov_b32_e32 v1, v53
	v_mov_b32_e32 v3, v52
	v_pk_add_f32 v[0:1], v[0:1], v[2:3]
	v_mov_b32_e32 v2, v62
	v_mov_b32_e32 v3, v54
	v_pk_add_f32 v[0:1], v[2:3], v[0:1]
	v_mov_b32_e32 v2, v63
	v_mov_b32_e32 v3, v55
	v_pk_add_f32 v[0:1], v[2:3], v[0:1]
	v_cmp_lt_i32_e32 vcc, v97, v95
	v_add_f32_e32 v1, v1, v4
	v_add_f32_e32 v0, v0, v1
	v_cndmask_b32_e32 v1, v110, v97, vcc
	v_lshlrev_b32_e32 v97, 2, v1
	v_cmp_lt_i32_e32 vcc, v99, v95
	s_movk_i32 s15, 0xfff
	s_mov_b64 s[16:17], 0x2000
	s_waitcnt lgkmcnt(0)
	v_mov_b32_e32 v1, v0
	s_nop 1
	v_permlane32_swap_b32_e32 v1, v0
	v_add_f32_e32 v0, v0, v1
	v_cndmask_b32_e32 v1, v110, v99, vcc
	v_lshlrev_b32_e32 v99, 2, v1
	v_cmp_lt_i32_e32 vcc, v101, v95
	s_waitcnt lgkmcnt(0)
	v_mov_b32_e32 v1, v0
	s_nop 1
	v_permlane16_swap_b32_e32 v1, v0
	v_add_f32_e32 v0, v0, v1
	v_cndmask_b32_e32 v1, v110, v101, vcc
	v_lshlrev_b32_e32 v101, 2, v1
	v_cmp_lt_i32_e32 vcc, v103, v95
	s_waitcnt lgkmcnt(0)
	s_nop 1
	v_add_f32_dpp v0, v0, v0 row_mirror row_mask:0xf bank_mask:0xf
	v_cndmask_b32_e32 v1, v110, v103, vcc
	v_lshlrev_b32_e32 v103, 2, v1
	v_cmp_lt_i32_e32 vcc, v105, v95
	s_waitcnt lgkmcnt(0)
	s_nop 1
	v_add_f32_dpp v0, v0, v0 row_half_mirror row_mask:0xf bank_mask:0xf
	v_cndmask_b32_e32 v1, v110, v105, vcc
	v_lshlrev_b32_e32 v105, 2, v1
	v_cmp_lt_i32_e32 vcc, v107, v95
	s_waitcnt lgkmcnt(0)
	s_nop 1
	v_add_f32_dpp v0, v0, v0 quad_perm:[2,3,0,1] row_mask:0xf bank_mask:0xf
	v_cndmask_b32_e32 v1, v110, v107, vcc
	v_lshlrev_b32_e32 v95, 2, v1
	v_cmp_lt_i32_e32 vcc, s15, v88
	v_mov_b32_e32 v107, v161
	s_movk_i32 s15, 0x1fff
	s_waitcnt lgkmcnt(0)
	s_nop 1
	v_add_f32_dpp v0, v0, v0 quad_perm:[1,0,3,2] row_mask:0xf bank_mask:0xf
	v_mul_f32_e32 v6, 0x3a000000, v0
	v_ashrrev_i32_e32 v0, 10, v65
	v_add_u32_e32 v0, 1, v0
	v_cndmask_b32_e32 v0, 0, v0, vcc
	v_add_u32_e32 v0, s11, v0
	v_mul_i32_i24_e32 v0, 0x1800, v0
	v_ashrrev_i32_e32 v1, 31, v0
	v_lshl_add_u64 v[0:1], v[0:1], 2, s[48:49]
	v_lshl_add_u64 v[2:3], v[0:1], 0, s[16:17]
	s_waitcnt vmcnt(3)
	v_lshl_add_u64 v[18:19], v[0:1], 0, v[160:161]
	v_lshl_add_u64 v[4:5], v[2:3], 0, v[160:161]
	global_load_dwordx4 v[10:13], v[18:19], off
	global_load_dwordx4 v[14:17], v[4:5], off
	s_waitcnt vmcnt(4)
	v_pk_add_f32 v[20:21], v[32:33], v[6:7] op_sel_hi:[1,0] neg_lo:[0,1] neg_hi:[0,1]
	s_waitcnt vmcnt(3)
	v_pk_add_f32 v[26:27], v[36:37], v[6:7] op_sel_hi:[1,0] neg_lo:[0,1] neg_hi:[0,1]
	v_pk_mul_f32 v[8:9], v[20:21], v[20:21]
	v_pk_add_f32 v[22:23], v[34:35], v[6:7] op_sel_hi:[1,0] neg_lo:[0,1] neg_hi:[0,1]
	s_waitcnt vmcnt(2)
	v_pk_mul_f32 v[28:29], v[26:27], v[26:27]
	v_pk_add_f32 v[30:31], v[38:39], v[6:7] op_sel_hi:[1,0] neg_lo:[0,1] neg_hi:[0,1]
	v_pk_add_f32 v[34:35], v[40:41], v[6:7] op_sel_hi:[1,0] neg_lo:[0,1] neg_hi:[0,1]
	v_pk_add_f32 v[48:49], v[48:49], v[6:7] op_sel_hi:[1,0] neg_lo:[0,1] neg_hi:[0,1]
	v_pk_add_f32 v[56:57], v[56:57], v[6:7] op_sel_hi:[1,0] neg_lo:[0,1] neg_hi:[0,1]
	v_pk_mul_f32 v[24:25], v[22:23], v[22:23]
	v_pk_mul_f32 v[32:33], v[30:31], v[30:31]
	v_pk_mul_f32 v[36:37], v[34:35], v[34:35]
	v_pk_add_f32 v[38:39], v[42:43], v[6:7] op_sel_hi:[1,0] neg_lo:[0,1] neg_hi:[0,1]
	v_mov_b32_e32 v112, v57
	v_mov_b32_e32 v113, v49
	v_add_f32_e32 v28, v28, v29
	v_add_f32_e32 v8, v8, v9
	v_pk_mul_f32 v[40:41], v[38:39], v[38:39]
	v_pk_add_f32 v[50:51], v[50:51], v[6:7] op_sel_hi:[1,0] neg_lo:[0,1] neg_hi:[0,1]
	v_pk_add_f32 v[58:59], v[58:59], v[6:7] op_sel_hi:[1,0] neg_lo:[0,1] neg_hi:[0,1]
	v_mov_b32_e32 v4, v56
	v_mov_b32_e32 v5, v48
	v_pk_mul_f32 v[112:113], v[112:113], v[112:113]
	v_add_f32_e32 v28, v32, v28
	v_add_f32_e32 v8, v24, v8
	v_add_f32_e32 v9, v36, v37
	v_pk_add_f32 v[42:43], v[44:45], v[6:7] op_sel_hi:[1,0] neg_lo:[0,1] neg_hi:[0,1]
	v_pk_fma_f32 v[4:5], v[4:5], v[4:5], v[112:113]
	v_mov_b32_e32 v112, v58
	v_mov_b32_e32 v113, v50
	v_add_f32_e32 v28, v33, v28
	v_add_f32_e32 v8, v25, v8
	v_add_f32_e32 v9, v40, v9
	v_pk_mul_f32 v[44:45], v[42:43], v[42:43]
	v_pk_add_f32 v[46:47], v[46:47], v[6:7] op_sel_hi:[1,0] neg_lo:[0,1] neg_hi:[0,1]
	v_mov_b32_e32 v114, v59
	v_mov_b32_e32 v115, v51
	v_pk_fma_f32 v[4:5], v[112:113], v[112:113], v[4:5]
	v_add_f32_e32 v8, v8, v28
	v_add_f32_e32 v9, v41, v9
	v_pk_mul_f32 v[110:111], v[46:47], v[46:47]
	v_pk_fma_f32 v[112:113], v[114:115], v[114:115], v[4:5]
	v_pk_add_f32 v[52:53], v[52:53], v[6:7] op_sel_hi:[1,0] neg_lo:[0,1] neg_hi:[0,1]
	v_pk_add_f32 v[4:5], v[60:61], v[6:7] op_sel_hi:[1,0] neg_lo:[0,1] neg_hi:[0,1]
	v_add_f32_e32 v8, v9, v8
	v_add_f32_e32 v9, v44, v45
	v_pk_add_f32 v[54:55], v[54:55], v[6:7] op_sel_hi:[1,0] neg_lo:[0,1] neg_hi:[0,1]
	v_pk_add_f32 v[6:7], v[62:63], v[6:7] op_sel_hi:[1,0] neg_lo:[0,1] neg_hi:[0,1]
	v_mov_b32_e32 v62, v5
	v_mov_b32_e32 v63, v53
	v_add_f32_e32 v9, v110, v9
	v_mov_b32_e32 v60, v4
	v_mov_b32_e32 v61, v52
	v_pk_mul_f32 v[62:63], v[62:63], v[62:63]
	v_add_f32_e32 v9, v111, v9
	v_pk_fma_f32 v[60:61], v[60:61], v[60:61], v[62:63]
	v_mov_b32_e32 v62, v6
	v_mov_b32_e32 v63, v54
	v_add_f32_e32 v8, v9, v8
	v_mov_b32_e32 v114, v7
	v_mov_b32_e32 v115, v55
	v_pk_fma_f32 v[60:61], v[62:63], v[62:63], v[60:61]
	v_add_f32_e32 v8, v113, v8
	v_pk_fma_f32 v[60:61], v[114:115], v[114:115], v[60:61]
	v_add_f32_e32 v8, v112, v8
	v_add_f32_e32 v8, v61, v8
	v_add_f32_e32 v8, v60, v8
	v_mov_b32_e32 v97, v161
	v_readlane_b32 s16, v251, 22
	v_readlane_b32 s17, v251, 23
	s_waitcnt lgkmcnt(0)
	v_mov_b32_e32 v9, v8
	s_nop 1
	v_permlane32_swap_b32_e32 v9, v8
	v_add_f32_e32 v8, v8, v9
	v_mov_b32_e32 v99, v161
	v_lshl_add_u64 v[90:91], v[90:91], 0, s[16:17]
	v_readlane_b32 s16, v251, 26
	v_readlane_b32 s17, v251, 27
	s_waitcnt lgkmcnt(0)
	v_mov_b32_e32 v9, v8
	s_nop 1
	v_permlane16_swap_b32_e32 v9, v8
	v_add_f32_e32 v8, v8, v9
	s_waitcnt vmcnt(0)
	v_pk_add_f32 v[14:15], v[14:15], 1.0 op_sel_hi:[1,0]
	v_pk_add_f32 v[16:17], v[16:17], 1.0 op_sel_hi:[1,0]
	v_mov_b32_e32 v101, v161
	v_lshl_add_u64 v[88:89], v[88:89], 0, s[16:17]
	s_waitcnt lgkmcnt(0)
	s_nop 1
	v_add_f32_dpp v8, v8, v8 row_mirror row_mask:0xf bank_mask:0xf
	v_mov_b32_e32 v103, v161
	v_readlane_b32 s16, v251, 28
	v_readlane_b32 s17, v251, 29
	s_waitcnt lgkmcnt(0)
	s_nop 1
	v_add_f32_dpp v8, v8, v8 row_half_mirror row_mask:0xf bank_mask:0xf
	v_mov_b32_e32 v105, v161
	v_lshl_add_u64 v[92:93], v[92:93], 0, s[16:17]
	s_waitcnt lgkmcnt(0)
	s_nop 1
	v_add_f32_dpp v24, v8, v8 quad_perm:[2,3,0,1] row_mask:0xf bank_mask:0xf
	v_lshlrev_b64 v[8:9], 12, v[108:109]
	v_lshl_add_u64 v[8:9], v[86:87], 0, v[8:9]
	v_mov_b32_e32 v95, v161
	s_waitcnt lgkmcnt(0)
	s_nop 1
	v_add_f32_dpp v24, v24, v24 quad_perm:[1,0,3,2] row_mask:0xf bank_mask:0xf
	v_fmamk_f32 v24, v24, 0x3a000000, v190
	v_mul_f32_e32 v25, 0x4b800000, v24
	v_cmp_gt_f32_e32 vcc, s79, v24
	s_nop 1
	v_cndmask_b32_e32 v24, v24, v25, vcc
	v_rsq_f32_e32 v28, v24
	v_lshl_add_u64 v[24:25], v[2:3], 0, v[94:95]
	v_mul_f32_e32 v29, 0x45800000, v28
	v_cndmask_b32_e32 v28, v28, v29, vcc
	v_pk_mul_f32 v[20:21], v[20:21], v[28:29] op_sel_hi:[1,0]
	v_pk_mul_f32 v[4:5], v[4:5], v[28:29] op_sel_hi:[1,0]
	v_pk_fma_f32 v[10:11], v[14:15], v[20:21], v[10:11]
	v_pk_mul_f32 v[14:15], v[22:23], v[28:29] op_sel_hi:[1,0]
	v_pk_mul_f32 v[22:23], v[26:27], v[28:29] op_sel_hi:[1,0]
	v_pk_fma_f32 v[12:13], v[16:17], v[14:15], v[12:13]
	v_bfe_u32 v16, v11, 16, 1
	v_bfe_u32 v14, v13, 16, 1
	v_bfe_u32 v15, v12, 16, 1
	v_bfe_u32 v17, v10, 16, 1
	v_add3_u32 v10, v10, v17, s94
	v_add3_u32 v16, v11, v16, s94
	v_add3_u32 v11, v12, v15, s94
	v_add3_u32 v12, v13, v14, s94
	v_perm_b32 v11, v12, v11, s95
	v_perm_b32 v10, v16, v10, s95
	global_store_dwordx2 v[8:9], v[10:11], off
	global_load_dwordx4 v[10:13], v[24:25], off
	s_nop 0
	global_load_dwordx4 v[14:17], v[18:19], off offset:1024
	v_lshl_add_u64 v[20:21], v[2:3], 0, v[96:97]
	v_pk_mul_f32 v[24:25], v[38:39], v[28:29] op_sel_hi:[1,0]
	v_pk_mul_f32 v[6:7], v[6:7], v[28:29] op_sel_hi:[1,0]
	v_cmp_lt_i32_e32 vcc, s15, v88
	s_or_b64 s[38:39], vcc, s[38:39]
	s_waitcnt vmcnt(1)
	v_pk_add_f32 v[10:11], v[10:11], 1.0 op_sel_hi:[1,0]
	s_waitcnt vmcnt(0)
	v_pk_fma_f32 v[10:11], v[10:11], v[22:23], v[14:15]
	v_pk_mul_f32 v[14:15], v[30:31], v[28:29] op_sel_hi:[1,0]
	v_pk_add_f32 v[12:13], v[12:13], 1.0 op_sel_hi:[1,0]
	v_pk_mul_f32 v[22:23], v[34:35], v[28:29] op_sel_hi:[1,0]
	v_pk_fma_f32 v[12:13], v[12:13], v[14:15], v[16:17]
	v_bfe_u32 v14, v11, 16, 1
	v_bfe_u32 v15, v10, 16, 1
	v_bfe_u32 v16, v13, 16, 1
	v_bfe_u32 v17, v12, 16, 1
	v_add3_u32 v12, v12, v17, s94
	v_add3_u32 v13, v13, v16, s94
	v_add3_u32 v10, v10, v15, s94
	v_add3_u32 v11, v11, v14, s94
	v_perm_b32 v10, v11, v10, s95
	v_perm_b32 v11, v13, v12, s95
	global_store_dwordx2 v[8:9], v[10:11], off offset:512
	global_load_dwordx4 v[10:13], v[20:21], off
	s_nop 0
	global_load_dwordx4 v[14:17], v[18:19], off offset:2048
	v_lshl_add_u64 v[20:21], v[2:3], 0, v[98:99]
	s_waitcnt vmcnt(1)
	v_pk_add_f32 v[10:11], v[10:11], 1.0 op_sel_hi:[1,0]
	v_pk_add_f32 v[12:13], v[12:13], 1.0 op_sel_hi:[1,0]
	s_waitcnt vmcnt(0)
	v_pk_fma_f32 v[10:11], v[10:11], v[22:23], v[14:15]
	v_pk_fma_f32 v[12:13], v[12:13], v[24:25], v[16:17]
	v_bfe_u32 v14, v11, 16, 1
	v_bfe_u32 v15, v10, 16, 1
	v_bfe_u32 v16, v13, 16, 1
	v_bfe_u32 v17, v12, 16, 1
	v_add3_u32 v12, v12, v17, s94
	v_add3_u32 v13, v13, v16, s94
	v_add3_u32 v10, v10, v15, s94
	v_add3_u32 v11, v11, v14, s94
	v_perm_b32 v10, v11, v10, s95
	v_perm_b32 v11, v13, v12, s95
	global_store_dwordx2 v[8:9], v[10:11], off offset:1024
	global_load_dwordx4 v[10:13], v[20:21], off
	s_nop 0
	global_load_dwordx4 v[14:17], v[18:19], off offset:3072
	v_pk_mul_f32 v[20:21], v[42:43], v[28:29] op_sel_hi:[1,0]
	v_pk_mul_f32 v[22:23], v[46:47], v[28:29] op_sel_hi:[1,0]
	v_lshl_add_u64 v[18:19], v[2:3], 0, v[100:101]
	s_waitcnt vmcnt(1)
	v_pk_add_f32 v[10:11], v[10:11], 1.0 op_sel_hi:[1,0]
	v_pk_add_f32 v[12:13], v[12:13], 1.0 op_sel_hi:[1,0]
	s_waitcnt vmcnt(0)
	v_pk_fma_f32 v[10:11], v[20:21], v[10:11], v[14:15]
	v_pk_fma_f32 v[12:13], v[22:23], v[12:13], v[16:17]
	v_bfe_u32 v14, v11, 16, 1
	v_bfe_u32 v15, v10, 16, 1
	v_bfe_u32 v16, v13, 16, 1
	v_bfe_u32 v17, v12, 16, 1
	v_add3_u32 v12, v12, v17, s94
	v_add3_u32 v13, v13, v16, s94
	v_add3_u32 v10, v10, v15, s94
	v_add3_u32 v11, v11, v14, s94
	v_perm_b32 v10, v11, v10, s95
	v_perm_b32 v11, v13, v12, s95
	global_store_dwordx2 v[8:9], v[10:11], off offset:1536
	global_load_dwordx4 v[10:13], v[18:19], off
	v_lshl_add_u64 v[14:15], v[0:1], 0, v[100:101]
	global_load_dwordx4 v[14:17], v[14:15], off
	v_pk_mul_f32 v[20:21], v[48:49], v[28:29] op_sel_hi:[1,0]
	v_pk_mul_f32 v[22:23], v[50:51], v[28:29] op_sel_hi:[1,0]
	v_lshl_add_u64 v[18:19], v[2:3], 0, v[102:103]
	s_waitcnt vmcnt(1)
	v_pk_add_f32 v[10:11], v[10:11], 1.0 op_sel_hi:[1,0]
	v_pk_add_f32 v[12:13], v[12:13], 1.0 op_sel_hi:[1,0]
	s_waitcnt vmcnt(0)
	v_pk_fma_f32 v[10:11], v[20:21], v[10:11], v[14:15]
	v_pk_fma_f32 v[12:13], v[22:23], v[12:13], v[16:17]
	v_bfe_u32 v14, v11, 16, 1
	v_bfe_u32 v15, v10, 16, 1
	v_bfe_u32 v16, v13, 16, 1
	v_bfe_u32 v17, v12, 16, 1
	v_add3_u32 v12, v12, v17, s94
	v_add3_u32 v13, v13, v16, s94
	v_add3_u32 v10, v10, v15, s94
	v_add3_u32 v11, v11, v14, s94
	v_perm_b32 v10, v11, v10, s95
	v_perm_b32 v11, v13, v12, s95
	global_store_dwordx2 v[8:9], v[10:11], off offset:2048
	global_load_dwordx4 v[10:13], v[18:19], off
	v_lshl_add_u64 v[14:15], v[0:1], 0, v[102:103]
	global_load_dwordx4 v[14:17], v[14:15], off
	v_pk_mul_f32 v[20:21], v[56:57], v[28:29] op_sel_hi:[1,0]
	v_pk_mul_f32 v[22:23], v[58:59], v[28:29] op_sel_hi:[1,0]
	v_lshl_add_u64 v[18:19], v[2:3], 0, v[104:105]
	v_lshl_add_u64 v[2:3], v[2:3], 0, v[106:107]
	s_waitcnt vmcnt(1)
	v_pk_add_f32 v[10:11], v[10:11], 1.0 op_sel_hi:[1,0]
	v_pk_add_f32 v[12:13], v[12:13], 1.0 op_sel_hi:[1,0]
	s_waitcnt vmcnt(0)
	v_pk_fma_f32 v[10:11], v[20:21], v[10:11], v[14:15]
	v_pk_fma_f32 v[12:13], v[22:23], v[12:13], v[16:17]
	v_bfe_u32 v14, v11, 16, 1
	v_bfe_u32 v15, v10, 16, 1
	v_bfe_u32 v16, v13, 16, 1
	v_bfe_u32 v17, v12, 16, 1
	v_add3_u32 v12, v12, v17, s94
	v_add3_u32 v13, v13, v16, s94
	v_add3_u32 v10, v10, v15, s94
	v_add3_u32 v11, v11, v14, s94
	v_perm_b32 v10, v11, v10, s95
	v_perm_b32 v11, v13, v12, s95
	global_store_dwordx2 v[8:9], v[10:11], off offset:2560
	global_load_dwordx4 v[10:13], v[18:19], off
	v_lshl_add_u64 v[14:15], v[0:1], 0, v[104:105]
	global_load_dwordx4 v[14:17], v[14:15], off
	v_pk_mul_f32 v[18:19], v[52:53], v[28:29] op_sel_hi:[1,0]
	v_pk_mul_f32 v[20:21], v[54:55], v[28:29] op_sel_hi:[1,0]
	v_lshl_add_u64 v[0:1], v[0:1], 0, v[106:107]
	s_waitcnt vmcnt(1)
	v_pk_add_f32 v[10:11], v[10:11], 1.0 op_sel_hi:[1,0]
	v_pk_add_f32 v[12:13], v[12:13], 1.0 op_sel_hi:[1,0]
	s_waitcnt vmcnt(0)
	v_pk_fma_f32 v[10:11], v[18:19], v[10:11], v[14:15]
	v_pk_fma_f32 v[12:13], v[20:21], v[12:13], v[16:17]
	v_bfe_u32 v14, v11, 16, 1
	v_bfe_u32 v15, v10, 16, 1
	v_bfe_u32 v16, v13, 16, 1
	v_bfe_u32 v17, v12, 16, 1
	v_add3_u32 v12, v12, v17, s94
	v_add3_u32 v13, v13, v16, s94
	v_add3_u32 v10, v10, v15, s94
	v_add3_u32 v11, v11, v14, s94
	v_perm_b32 v10, v11, v10, s95
	v_perm_b32 v11, v13, v12, s95
	global_store_dwordx2 v[8:9], v[10:11], off offset:3072
	global_load_dwordx4 v[10:13], v[2:3], off
	s_waitcnt vmcnt(0)
	v_pk_add_f32 v[10:11], v[10:11], 1.0 op_sel_hi:[1,0]
	global_load_dwordx4 v[0:3], v[0:1], off
	v_pk_add_f32 v[12:13], v[12:13], 1.0 op_sel_hi:[1,0]
	s_waitcnt vmcnt(0)
	v_pk_fma_f32 v[0:1], v[4:5], v[10:11], v[0:1]
	v_pk_fma_f32 v[2:3], v[6:7], v[12:13], v[2:3]
	v_bfe_u32 v4, v1, 16, 1
	v_bfe_u32 v5, v0, 16, 1
	v_bfe_u32 v6, v3, 16, 1
	v_bfe_u32 v7, v2, 16, 1
	v_add3_u32 v2, v2, v7, s94
	v_add3_u32 v3, v3, v6, s94
	v_add3_u32 v0, v0, v5, s94
	v_add3_u32 v1, v1, v4, s94
	v_perm_b32 v0, v1, v0, s95
	v_perm_b32 v1, v3, v2, s95
	global_store_dwordx2 v[8:9], v[0:1], off offset:3584
	s_andn2_b64 exec, exec, s[38:39]
	s_cbranch_execz .LBB0_437

.LBB0_433:
	s_mov_b64 s[40:41], -1
	s_and_b64 vcc, exec, s[72:73]
	s_cbranch_vccz .LBB0_435
	s_waitcnt vmcnt(7)
	v_add_f32_e32 v32, v1, v0
	v_add_f32_e32 v32, v2, v32
	s_waitcnt vmcnt(6)
	v_add_f32_e32 v33, v5, v4
	v_add_f32_e32 v32, v3, v32
	v_add_f32_e32 v33, v6, v33
	v_add_f32_e32 v32, 0, v32
	v_add_f32_e32 v33, v7, v33
	v_add_f32_e32 v32, v33, v32
	s_waitcnt vmcnt(5)
	v_add_f32_e32 v33, v9, v8
	v_add_f32_e32 v33, v10, v33
	v_add_f32_e32 v33, v11, v33
	v_add_f32_e32 v32, v33, v32
	s_waitcnt vmcnt(4)
	v_add_f32_e32 v33, v13, v12
	v_add_f32_e32 v33, v14, v33
	v_add_f32_e32 v33, v15, v33
	v_add_f32_e32 v36, v33, v32
	s_waitcnt vmcnt(2)
	v_mov_b32_e32 v32, v21
	v_mov_b32_e32 v33, v17
	v_mov_b32_e32 v34, v20
	v_mov_b32_e32 v35, v16
	v_pk_add_f32 v[32:33], v[32:33], v[34:35]
	v_mov_b32_e32 v34, v22
	v_mov_b32_e32 v35, v18
	v_pk_add_f32 v[32:33], v[34:35], v[32:33]
	v_mov_b32_e32 v34, v23
	v_mov_b32_e32 v35, v19
	v_pk_add_f32 v[32:33], v[34:35], v[32:33]
	s_waitcnt vmcnt(0)
	v_mov_b32_e32 v34, v28
	v_add_f32_e32 v33, v33, v36
	v_add_f32_e32 v36, v32, v33
	v_mov_b32_e32 v32, v29
	v_mov_b32_e32 v33, v25
	v_mov_b32_e32 v35, v24
	v_pk_add_f32 v[32:33], v[32:33], v[34:35]
	v_mov_b32_e32 v34, v30
	v_mov_b32_e32 v35, v26
	v_pk_add_f32 v[32:33], v[34:35], v[32:33]
	v_mov_b32_e32 v34, v31
	v_mov_b32_e32 v35, v27
	v_pk_add_f32 v[32:33], v[34:35], v[32:33]
	v_xor_b32_e32 v97, 32, v199
	v_add_f32_e32 v33, v33, v36
	v_add_f32_e32 v32, v32, v33
	v_and_b32_e32 v33, 64, v199
	v_add_u32_e32 v95, 64, v33
	v_cmp_lt_i32_e32 vcc, v97, v95
	v_xor_b32_e32 v99, 16, v199
	v_xor_b32_e32 v101, 8, v199
	v_cndmask_b32_e32 v33, v199, v97, vcc
	v_lshlrev_b32_e32 v136, 2, v33
	v_cmp_lt_i32_e32 vcc, v99, v95
	v_xor_b32_e32 v103, 4, v199
	v_xor_b32_e32 v105, 2, v199
	v_xor_b32_e32 v107, 1, v199
	s_waitcnt lgkmcnt(0)
	v_mov_b32_e32 v33, v32
	s_nop 1
	v_permlane32_swap_b32_e32 v33, v32
	v_add_f32_e32 v32, v32, v33
	v_cndmask_b32_e32 v33, v199, v99, vcc
	v_lshlrev_b32_e32 v137, 2, v33
	v_cmp_lt_i32_e32 vcc, v101, v95
	s_waitcnt lgkmcnt(0)
	v_mov_b32_e32 v33, v32
	s_nop 1
	v_permlane16_swap_b32_e32 v33, v32
	v_add_f32_e32 v32, v32, v33
	v_cndmask_b32_e32 v33, v199, v101, vcc
	v_lshlrev_b32_e32 v138, 2, v33
	v_cmp_lt_i32_e32 vcc, v103, v95
	s_waitcnt lgkmcnt(0)
	s_nop 1
	v_add_f32_dpp v32, v32, v32 row_mirror row_mask:0xf bank_mask:0xf
	v_cndmask_b32_e32 v33, v199, v103, vcc
	v_lshlrev_b32_e32 v139, 2, v33
	v_cmp_lt_i32_e32 vcc, v105, v95
	s_waitcnt lgkmcnt(0)
	s_nop 1
	v_add_f32_dpp v32, v32, v32 row_half_mirror row_mask:0xf bank_mask:0xf
	v_cndmask_b32_e32 v33, v199, v105, vcc
	v_lshlrev_b32_e32 v140, 2, v33
	v_cmp_lt_i32_e32 vcc, v107, v95
	s_waitcnt lgkmcnt(0)
	s_nop 1
	v_add_f32_dpp v32, v32, v32 quad_perm:[2,3,0,1] row_mask:0xf bank_mask:0xf
	v_cndmask_b32_e32 v33, v199, v107, vcc
	v_lshlrev_b32_e32 v141, 2, v33
	s_waitcnt lgkmcnt(0)
	s_nop 1
	v_add_f32_dpp v32, v32, v32 quad_perm:[1,0,3,2] row_mask:0xf bank_mask:0xf
	v_mul_f32_e32 v40, 0x3a000000, v32
	v_pk_add_f32 v[116:117], v[28:29], v[40:41] op_sel_hi:[1,0] neg_lo:[0,1] neg_hi:[0,1]
	v_pk_add_f32 v[110:111], v[24:25], v[40:41] op_sel_hi:[1,0] neg_lo:[0,1] neg_hi:[0,1]
	v_mov_b32_e32 v38, v117
	v_mov_b32_e32 v39, v111
	v_pk_add_f32 v[114:115], v[30:31], v[40:41] op_sel_hi:[1,0] neg_lo:[0,1] neg_hi:[0,1]
	v_pk_add_f32 v[108:109], v[26:27], v[40:41] op_sel_hi:[1,0] neg_lo:[0,1] neg_hi:[0,1]
	v_mov_b32_e32 v36, v116
	v_mov_b32_e32 v37, v110
	v_pk_mul_f32 v[38:39], v[38:39], v[38:39]
	v_pk_add_f32 v[62:63], v[20:21], v[40:41] op_sel_hi:[1,0] neg_lo:[0,1] neg_hi:[0,1]
	v_pk_add_f32 v[58:59], v[16:17], v[40:41] op_sel_hi:[1,0] neg_lo:[0,1] neg_hi:[0,1]
	v_mov_b32_e32 v32, v114
	v_mov_b32_e32 v33, v108
	v_pk_fma_f32 v[36:37], v[36:37], v[36:37], v[38:39]
	v_mov_b32_e32 v38, v63
	v_mov_b32_e32 v39, v59
	v_mov_b32_e32 v34, v115
	v_mov_b32_e32 v35, v109
	v_pk_fma_f32 v[32:33], v[32:33], v[32:33], v[36:37]
	v_pk_add_f32 v[60:61], v[22:23], v[40:41] op_sel_hi:[1,0] neg_lo:[0,1] neg_hi:[0,1]
	v_pk_add_f32 v[56:57], v[18:19], v[40:41] op_sel_hi:[1,0] neg_lo:[0,1] neg_hi:[0,1]
	v_mov_b32_e32 v36, v62
	v_mov_b32_e32 v37, v58
	v_pk_mul_f32 v[38:39], v[38:39], v[38:39]
	v_pk_fma_f32 v[42:43], v[34:35], v[34:35], v[32:33]
	v_mov_b32_e32 v32, v60
	v_mov_b32_e32 v33, v56
	v_pk_fma_f32 v[36:37], v[36:37], v[36:37], v[38:39]
	v_mov_b32_e32 v34, v61
	v_mov_b32_e32 v35, v57
	v_pk_fma_f32 v[32:33], v[32:33], v[32:33], v[36:37]
	v_pk_add_f32 v[126:127], v[4:5], v[40:41] op_sel_hi:[1,0] neg_lo:[0,1] neg_hi:[0,1]
	v_pk_fma_f32 v[44:45], v[34:35], v[34:35], v[32:33]
	global_load_dwordx4 v[32:35], v[66:67], off
	global_load_dwordx4 v[36:39], v[68:69], off
	v_pk_add_f32 v[122:123], v[6:7], v[40:41] op_sel_hi:[1,0] neg_lo:[0,1] neg_hi:[0,1]
	v_pk_mul_f32 v[128:129], v[126:127], v[126:127]
	v_pk_add_f32 v[52:53], v[14:15], v[40:41] op_sel_hi:[1,0] neg_lo:[0,1] neg_hi:[0,1]
	v_pk_add_f32 v[54:55], v[12:13], v[40:41] op_sel_hi:[1,0] neg_lo:[0,1] neg_hi:[0,1]
	v_pk_add_f32 v[50:51], v[10:11], v[40:41] op_sel_hi:[1,0] neg_lo:[0,1] neg_hi:[0,1]
	v_pk_add_f32 v[118:119], v[8:9], v[40:41] op_sel_hi:[1,0] neg_lo:[0,1] neg_hi:[0,1]
	v_pk_mul_f32 v[124:125], v[122:123], v[122:123]
	v_pk_add_f32 v[130:131], v[2:3], v[40:41] op_sel_hi:[1,0] neg_lo:[0,1] neg_hi:[0,1]
	v_pk_add_f32 v[40:41], v[0:1], v[40:41] op_sel_hi:[1,0] neg_lo:[0,1] neg_hi:[0,1]
	v_add_f32_e32 v128, v128, v129
	v_pk_mul_f32 v[134:135], v[40:41], v[40:41]
	v_add_f32_e32 v124, v124, v128
	v_pk_mul_f32 v[120:121], v[118:119], v[118:119]
	v_pk_mul_f32 v[132:133], v[130:131], v[130:131]
	v_add_f32_e32 v124, v125, v124
	v_add_f32_e32 v125, v134, v135
	v_pk_mul_f32 v[48:49], v[54:55], v[54:55]
	v_pk_mul_f32 v[112:113], v[50:51], v[50:51]
	v_add_f32_e32 v125, v132, v125
	v_add_f32_e32 v120, v120, v121
	v_pk_mul_f32 v[46:47], v[52:53], v[52:53]
	v_add_f32_e32 v125, v133, v125
	v_add_f32_e32 v112, v112, v120
	v_add_f32_e32 v48, v48, v49
	v_add_f32_e32 v124, v125, v124
	v_add_f32_e32 v112, v113, v112
	v_add_f32_e32 v46, v46, v48
	v_add_f32_e32 v112, v112, v124
	v_add_f32_e32 v46, v47, v46
	v_add_f32_e32 v46, v46, v112
	v_add_f32_e32 v45, v45, v46
	v_add_f32_e32 v44, v44, v45
	v_add_f32_e32 v43, v43, v44
	v_add_f32_e32 v42, v42, v43
	s_waitcnt lgkmcnt(0)
	v_mov_b32_e32 v43, v42
	s_nop 1
	v_permlane32_swap_b32_e32 v43, v42
	v_add_f32_e32 v42, v42, v43
	s_waitcnt lgkmcnt(0)
	v_mov_b32_e32 v43, v42
	s_nop 1
	v_permlane16_swap_b32_e32 v43, v42
	v_add_f32_e32 v42, v42, v43
	s_waitcnt lgkmcnt(0)
	s_nop 1
	v_add_f32_dpp v42, v42, v42 row_mirror row_mask:0xf bank_mask:0xf
	s_waitcnt lgkmcnt(0)
	s_nop 1
	v_add_f32_dpp v42, v42, v42 row_half_mirror row_mask:0xf bank_mask:0xf
	s_waitcnt lgkmcnt(0)
	s_nop 1
	v_add_f32_dpp v42, v42, v42 quad_perm:[2,3,0,1] row_mask:0xf bank_mask:0xf
	s_waitcnt lgkmcnt(0)
	s_nop 1
	v_add_f32_dpp v42, v42, v42 quad_perm:[1,0,3,2] row_mask:0xf bank_mask:0xf
	v_fmamk_f32 v42, v42, 0x3a000000, v190
	v_mul_f32_e32 v43, 0x4b800000, v42
	v_cmp_gt_f32_e32 vcc, s79, v42
	s_nop 1
	v_cndmask_b32_e32 v42, v42, v43, vcc
	v_rsq_f32_e32 v42, v42
	s_nop 0
	v_mul_f32_e32 v43, 0x45800000, v42
	v_cndmask_b32_e32 v120, v42, v43, vcc
	v_pk_mul_f32 v[40:41], v[40:41], v[120:121] op_sel_hi:[1,0]
	v_pk_mul_f32 v[44:45], v[126:127], v[120:121] op_sel_hi:[1,0]
	s_waitcnt vmcnt(0)
	v_pk_fma_f32 v[32:33], v[32:33], v[40:41], v[36:37]
	v_pk_mul_f32 v[36:37], v[130:131], v[120:121] op_sel_hi:[1,0]
	v_pk_mul_f32 v[46:47], v[122:123], v[120:121] op_sel_hi:[1,0]
	v_pk_fma_f32 v[34:35], v[34:35], v[36:37], v[38:39]
	global_store_dwordx4 v[92:93], v[32:35], off offset:-4096
	global_load_dwordx4 v[36:39], v[66:67], off offset:1024
	global_load_dwordx4 v[40:43], v[68:69], off offset:1024
	v_pk_mul_f32 v[48:49], v[118:119], v[120:121] op_sel_hi:[1,0]
	v_pk_mul_f32 v[50:51], v[50:51], v[120:121] op_sel_hi:[1,0]
	v_pk_mul_f32 v[54:55], v[54:55], v[120:121] op_sel_hi:[1,0]
	v_pk_mul_f32 v[52:53], v[52:53], v[120:121] op_sel_hi:[1,0]
	v_pk_mul_f32 v[58:59], v[58:59], v[120:121] op_sel_hi:[1,0]
	v_pk_mul_f32 v[56:57], v[56:57], v[120:121] op_sel_hi:[1,0]
	v_pk_mul_f32 v[62:63], v[62:63], v[120:121] op_sel_hi:[1,0]
	v_pk_mul_f32 v[60:61], v[60:61], v[120:121] op_sel_hi:[1,0]
	v_pk_mul_f32 v[110:111], v[110:111], v[120:121] op_sel_hi:[1,0]
	v_pk_mul_f32 v[108:109], v[108:109], v[120:121] op_sel_hi:[1,0]
	v_pk_mul_f32 v[116:117], v[116:117], v[120:121] op_sel_hi:[1,0]
	v_pk_mul_f32 v[114:115], v[114:115], v[120:121] op_sel_hi:[1,0]
	s_waitcnt vmcnt(0)
	v_pk_fma_f32 v[36:37], v[36:37], v[44:45], v[40:41]
	v_pk_fma_f32 v[38:39], v[38:39], v[46:47], v[42:43]
	global_store_dwordx4 v[92:93], v[36:39], off offset:-3072
	global_load_dwordx4 v[40:43], v[66:67], off offset:2048
	global_load_dwordx4 v[44:47], v[68:69], off offset:2048
	s_waitcnt vmcnt(0)
	v_pk_fma_f32 v[40:41], v[48:49], v[40:41], v[44:45]
	v_pk_fma_f32 v[42:43], v[50:51], v[42:43], v[46:47]
	global_store_dwordx4 v[92:93], v[40:43], off offset:-2048
	global_load_dwordx4 v[44:47], v[66:67], off offset:3072
	global_load_dwordx4 v[48:51], v[68:69], off offset:3072
	s_waitcnt vmcnt(0)
	v_pk_fma_f32 v[44:45], v[54:55], v[44:45], v[48:49]
	v_pk_fma_f32 v[46:47], v[52:53], v[46:47], v[50:51]
	global_store_dwordx4 v[92:93], v[44:47], off offset:-1024
	global_load_dwordx4 v[48:51], v[70:71], off
	global_load_dwordx4 v[52:55], v[72:73], off
	s_waitcnt vmcnt(0)
	v_pk_fma_f32 v[48:49], v[58:59], v[48:49], v[52:53]
	v_pk_fma_f32 v[50:51], v[56:57], v[50:51], v[54:55]
	global_store_dwordx4 v[92:93], v[48:51], off
	global_load_dwordx4 v[52:55], v[74:75], off
	global_load_dwordx4 v[56:59], v[76:77], off
	s_waitcnt vmcnt(0)
	v_pk_fma_f32 v[56:57], v[62:63], v[52:53], v[56:57]
	v_pk_fma_f32 v[58:59], v[60:61], v[54:55], v[58:59]
	global_store_dwordx4 v[92:93], v[56:59], off offset:1024
	global_load_dwordx4 v[52:55], v[78:79], off
	global_load_dwordx4 v[60:63], v[80:81], off
	s_waitcnt vmcnt(0)
	v_pk_fma_f32 v[52:53], v[110:111], v[52:53], v[60:61]
	v_pk_fma_f32 v[54:55], v[108:109], v[54:55], v[62:63]
	global_store_dwordx4 v[92:93], v[52:55], off offset:2048
	global_load_dwordx4 v[60:63], v[82:83], off
	global_load_dwordx4 v[110:113], v[84:85], off
	v_ashrrev_i32_e32 v109, 31, v88
	v_mov_b32_e32 v108, v88
	s_waitcnt vmcnt(0)
	v_pk_fma_f32 v[60:61], v[116:117], v[60:61], v[110:111]
	v_pk_fma_f32 v[62:63], v[114:115], v[62:63], v[112:113]
	global_store_dwordx4 v[92:93], v[60:63], off offset:3072
	v_mov_b32_e32 v110, v199
	s_cbranch_execnz .LBB0_428
	s_branch .LBB0_436

.LBB0_696:
	s_andn2_b64 vcc, exec, s[36:37]
	s_cbranch_vccnz .LBB0_703
	v_mov_b32_e32 v50, v189
	s_lshl_b32 s20, s19, 4
	v_readlane_b32 s38, v251, 47
	v_and_b32_e32 v0, 63, v50
	s_and_b32 s23, s20, 0x7f00
	s_lshl_b32 s36, s19, 6
	v_lshlrev_b32_e32 v0, 2, v0
	v_readlane_b32 s39, v251, 48
	s_add_i32 s37, s23, 0xffffc000
	s_and_b32 s20, s36, 0xc0
	s_nop 2
	global_load_dword v18, v0, s[38:39]
	global_load_dword v19, v0, s[38:39] offset:256
	global_load_dword v20, v0, s[38:39] offset:512
	global_load_dword v21, v0, s[38:39] offset:768
	v_ashrrev_i32_e32 v0, 2, v50
	s_or_b32 s20, s37, s20
	v_and_b32_e32 v184, -16, v0
	s_lshl_b32 s21, s19, 5
	v_and_b32_e32 v183, 15, v50
	v_add_u32_e32 v0, s20, v184
	s_and_b32 s21, s21, 0x180
	v_or_b32_e32 v0, v0, v183
	v_mov_b64_e32 v[16:17], s[6:7]
	v_mad_i64_i32 v[0:1], s[38:39], v0, s0, v[16:17]
	s_lshl_b32 s70, s21, 1
	v_lshl_add_u64 v[0:1], v[0:1], 0, s[70:71]
	v_and_b32_e32 v160, 48, v50
	v_lshl_add_u64 v[4:5], v[0:1], 0, v[160:161]
	s_movk_i32 s42, 0x1000
	v_add_co_u32_e32 v0, vcc, s42, v4
	v_mbcnt_hi_u32_b32 v151, -1, v194
	s_nop 0
	v_addc_co_u32_e32 v1, vcc, 0, v5, vcc
	global_load_dwordx4 v[0:3], v[0:1], off offset:1024
	v_and_b32_e32 v8, 64, v151
	s_mov_b64 s[38:39], 0x1400
	v_xor_b32_e32 v9, 32, v151
	v_add_u32_e32 v187, 64, v8
	v_lshl_add_u64 v[12:13], v[4:5], 0, s[38:39]
	v_xor_b32_e32 v10, 16, v151
	v_cmp_lt_i32_e32 vcc, v9, v187
	global_load_dwordx4 v[4:7], v[12:13], off offset:64
	v_xor_b32_e32 v11, 8, v151
	v_cndmask_b32_e32 v8, v151, v9, vcc
	v_cmp_lt_i32_e32 vcc, v10, v187
	v_lshlrev_b32_e32 v181, 2, v8
	s_mov_b32 s44, 0x3e000000
	v_cndmask_b32_e32 v9, v151, v10, vcc
	v_cmp_lt_i32_e32 vcc, v11, v187
	v_lshlrev_b32_e32 v182, 2, v9
	v_xor_b32_e32 v14, 4, v151
	v_cndmask_b32_e32 v10, v151, v11, vcc
	v_lshlrev_b32_e32 v24, 2, v10
	global_load_dwordx4 v[8:11], v[12:13], off offset:128
	v_cmp_lt_i32_e32 vcc, v14, v187
	v_xor_b32_e32 v15, 2, v151
	v_ashrrev_i32_e32 v185, 4, v50
	v_cndmask_b32_e32 v14, v151, v14, vcc
	v_lshlrev_b32_e32 v27, 2, v14
	v_cmp_lt_i32_e32 vcc, v15, v187
	v_lshlrev_b32_e32 v48, 4, v183
	v_mov_b32_e32 v49, v161
	v_cndmask_b32_e32 v15, v151, v15, vcc
	v_lshlrev_b32_e32 v28, 2, v15
	global_load_dwordx4 v[12:15], v[12:13], off offset:192
	s_barrier
	s_movk_i32 s39, 0x120
	v_mul_lo_u32 v211, v185, s39
	s_add_i32 s38, s23, 0xffffc040
	v_lshlrev_b32_e32 v186, 3, v50
	v_and_b32_e32 v84, 24, v186
	s_mov_b32 s22, 0
	v_mov_b32_e32 v142, 0xf149f2ca
	v_mov_b32_e32 v112, 0xf149f2ca
	s_waitcnt vmcnt(0)
	v_mul_f32_e32 v22, v18, v19
	ds_bpermute_b32 v25, v181, v22
	s_waitcnt vmcnt(4)
	v_mul_f32_e32 v23, v20, v21
	ds_bpermute_b32 v26, v181, v23
	s_waitcnt lgkmcnt(1)
	v_fmac_f32_e32 v25, v18, v19
	ds_bpermute_b32 v29, v182, v25
	s_waitcnt lgkmcnt(1)
	v_fmac_f32_e32 v26, v20, v21
	ds_bpermute_b32 v30, v182, v26
	s_waitcnt vmcnt(3)
	v_and_b32_e32 v19, 0xffff0000, v0
	v_lshlrev_b32_e32 v18, 16, v0
	v_and_b32_e32 v21, 0xffff0000, v1
	v_lshlrev_b32_e32 v20, 16, v1
	v_and_b32_e32 v1, 0xffff0000, v2
	v_lshlrev_b32_e32 v0, 16, v2
	v_and_b32_e32 v23, 0xffff0000, v3
	v_lshlrev_b32_e32 v22, 16, v3
	v_pk_mul_f32 v[2:3], v[18:19], s[44:45] op_sel_hi:[1,0]
	v_pk_mul_f32 v[0:1], v[0:1], s[44:45] op_sel_hi:[1,0]
	v_bfe_u32 v36, v2, 16, 1
	v_bfe_u32 v35, v3, 16, 1
	v_add3_u32 v51, v2, v36, s94
	s_waitcnt lgkmcnt(1)
	v_add_f32_e32 v2, v25, v29
	v_add3_u32 v52, v3, v35, s94
	s_waitcnt lgkmcnt(0)
	v_add_f32_e32 v3, v26, v30
	ds_bpermute_b32 v25, v24, v2
	ds_bpermute_b32 v24, v24, v3
	v_bfe_u32 v32, v0, 16, 1
	v_add3_u32 v55, v0, v32, s94
	v_pk_mul_f32 v[18:19], v[20:21], s[44:45] op_sel_hi:[1,0]
	s_waitcnt lgkmcnt(1)
	v_add_f32_e32 v0, v2, v25
	s_waitcnt lgkmcnt(0)
	v_add_f32_e32 v2, v3, v24
	ds_bpermute_b32 v3, v27, v0
	v_bfe_u32 v34, v18, 16, 1
	v_add3_u32 v53, v18, v34, s94
	ds_bpermute_b32 v18, v27, v2
	v_bfe_u32 v31, v1, 16, 1
	v_add3_u32 v56, v1, v31, s94
	s_waitcnt lgkmcnt(1)
	v_add_f32_e32 v205, v0, v3
	s_waitcnt vmcnt(2)
	v_and_b32_e32 v1, 0xffff0000, v4
	v_lshlrev_b32_e32 v0, 16, v4
	v_bfe_u32 v33, v19, 16, 1
	v_pk_mul_f32 v[0:1], v[0:1], s[44:45] op_sel_hi:[1,0]
	v_add3_u32 v54, v19, v33, s94
	s_waitcnt lgkmcnt(0)
	v_add_f32_e32 v207, v2, v18
	v_and_b32_e32 v19, 0xffff0000, v7
	v_lshlrev_b32_e32 v18, 16, v7
	v_and_b32_e32 v3, 0xffff0000, v5
	v_lshlrev_b32_e32 v2, 16, v5
	v_and_b32_e32 v5, 0xffff0000, v6
	v_lshlrev_b32_e32 v4, 16, v6
	v_pk_mul_f32 v[6:7], v[18:19], s[44:45] op_sel_hi:[1,0]
	v_cvt_pk_bf16_f32 v60, v0, v1
	s_waitcnt vmcnt(1)
	v_and_b32_e32 v1, 0xffff0000, v8
	v_lshlrev_b32_e32 v0, 16, v8
	v_pk_mul_f32 v[42:43], v[0:1], s[44:45] op_sel_hi:[1,0]
	v_and_b32_e32 v1, 0xffff0000, v9
	v_lshlrev_b32_e32 v0, 16, v9
	v_pk_mul_f32 v[8:9], v[0:1], s[44:45] op_sel_hi:[1,0]
	v_add_u32_e32 v0, s37, v185
	v_add_u32_e32 v18, 0x100, v50
	v_pk_mul_f32 v[20:21], v[22:23], s[44:45] op_sel_hi:[1,0]
	v_mad_i64_i32 v[0:1], s[40:41], v0, s0, v[16:17]
	v_ashrrev_i32_e32 v180, 4, v18
	v_bfe_u32 v22, v21, 16, 1
	v_pk_mul_f32 v[4:5], v[4:5], s[44:45] op_sel_hi:[1,0]
	v_lshl_add_u64 v[0:1], v[0:1], 0, s[70:71]
	v_add_u32_e32 v18, s37, v180
	v_add_u32_e32 v26, 0x200, v50
	v_bfe_u32 v23, v20, 16, 1
	v_add3_u32 v58, v21, v22, s94
	v_bfe_u32 v21, v4, 16, 1
	v_cvt_pk_bf16_f32 v65, v6, v7
	v_lshl_add_u64 v[0:1], v[0:1], 0, v[48:49]
	v_mad_i64_i32 v[18:19], s[40:41], v18, s0, v[16:17]
	v_ashrrev_i32_e32 v179, 4, v26
	v_add3_u32 v57, v20, v23, s94
	v_pk_mul_f32 v[2:3], v[2:3], s[44:45] op_sel_hi:[1,0]
	v_bfe_u32 v20, v5, 16, 1
	v_add3_u32 v63, v4, v21, s94
	v_add_co_u32_e32 v4, vcc, s42, v0
	v_lshl_add_u64 v[18:19], v[18:19], 0, s[70:71]
	v_add_u32_e32 v26, s37, v179
	v_add_u32_e32 v34, 0x300, v50
	v_add3_u32 v64, v5, v20, s94
	v_addc_co_u32_e32 v5, vcc, 0, v1, vcc
	v_lshl_add_u64 v[18:19], v[18:19], 0, v[48:49]
	v_mad_i64_i32 v[26:27], s[40:41], v26, s0, v[16:17]
	v_ashrrev_i32_e32 v178, 4, v34
	v_add_co_u32_e32 v22, vcc, s42, v18
	v_lshl_add_u64 v[26:27], v[26:27], 0, s[70:71]
	v_add_u32_e32 v34, s37, v178
	v_cvt_pk_bf16_f32 v61, v2, v3
	global_load_dwordx4 v[0:3], v[4:5], off offset:2048
	s_nop 0
	global_load_dwordx4 v[4:7], v[4:5], off offset:3072
	v_addc_co_u32_e32 v23, vcc, 0, v19, vcc
	v_lshl_add_u64 v[26:27], v[26:27], 0, v[48:49]
	v_mad_i64_i32 v[34:35], s[40:41], v34, s0, v[16:17]
	v_add_co_u32_e32 v30, vcc, s42, v26
	v_lshl_add_u64 v[34:35], v[34:35], 0, s[70:71]
	global_load_dwordx4 v[18:21], v[22:23], off offset:2048
	s_nop 0
	global_load_dwordx4 v[22:25], v[22:23], off offset:3072
	v_addc_co_u32_e32 v31, vcc, 0, v27, vcc
	v_lshl_add_u64 v[34:35], v[34:35], 0, v[48:49]
	v_add_co_u32_e32 v40, vcc, s42, v34
	ds_bpermute_b32 v206, v28, v205
	ds_bpermute_b32 v208, v28, v207
	global_load_dwordx4 v[26:29], v[30:31], off offset:2048
	s_nop 0
	global_load_dwordx4 v[30:33], v[30:31], off offset:3072
	v_addc_co_u32_e32 v41, vcc, 0, v35, vcc
	v_and_b32_e32 v39, 0xffff0000, v10
	global_load_dwordx4 v[34:37], v[40:41], off offset:2048
	v_lshlrev_b32_e32 v38, 16, v10
	v_pk_mul_f32 v[44:45], v[38:39], s[44:45] op_sel_hi:[1,0]
	global_load_dwordx4 v[38:41], v[40:41], off offset:3072
	v_bfe_u32 v69, v9, 16, 1
	v_bfe_u32 v70, v8, 16, 1
	v_add3_u32 v70, v8, v70, s94
	v_add3_u32 v69, v9, v69, s94
	s_waitcnt vmcnt(8)
	v_and_b32_e32 v9, 0xffff0000, v12
	v_lshlrev_b32_e32 v8, 16, v12
	v_pk_mul_f32 v[8:9], v[8:9], s[44:45] op_sel_hi:[1,0]
	s_movk_i32 s37, 0x110
	v_bfe_u32 v75, v9, 16, 1
	v_bfe_u32 v76, v8, 16, 1
	v_add3_u32 v75, v9, v75, s94
	v_lshrrev_b32_e32 v9, 2, v50
	v_add3_u32 v76, v8, v76, s94
	v_bfe_u32 v8, v50, 2, 2
	v_and_b32_e32 v204, 12, v9
	v_or_b32_e32 v8, v204, v8
	v_mul_u32_u24_e32 v83, 0x120, v8
	v_lshlrev_b32_e32 v8, 4, v50
	v_mul_lo_u32 v209, v185, s37
	v_and_b32_e32 v210, 0xf0, v8
	v_add3_u32 v8, s17, v209, v210
	v_mul_lo_u32 v212, v180, s37
	v_mul_lo_u32 v213, v180, s39
	v_mul_lo_u32 v214, v179, s37
	v_mul_lo_u32 v215, v179, s39
	v_mul_lo_u32 v216, v178, s37
	v_mul_lo_u32 v217, v178, s39
	v_and_b32_e32 v47, 0xffff0000, v11
	v_lshlrev_b32_e32 v46, 16, v11
	v_pk_mul_f32 v[10:11], v[46:47], s[44:45] op_sel_hi:[1,0]
	v_lshlrev_b32_e32 v12, 16, v14
	v_cvt_pk_bf16_f32 v74, v10, v11
	v_and_b32_e32 v11, 0xffff0000, v13
	v_lshlrev_b32_e32 v10, 16, v13
	v_and_b32_e32 v13, 0xffff0000, v14
	v_bfe_u32 v67, v45, 16, 1
	v_pk_mul_f32 v[12:13], v[12:13], s[44:45] op_sel_hi:[1,0]
	v_bfe_u32 v68, v44, 16, 1
	v_add3_u32 v67, v45, v67, s94
	v_bfe_u32 v71, v43, 16, 1
	v_bfe_u32 v72, v42, 16, 1
	v_add3_u32 v68, v44, v68, s94
	v_add3_u32 v72, v42, v72, s94
	v_add3_u32 v71, v43, v71, s94
	v_and_b32_e32 v43, 0xffff0000, v15
	v_lshlrev_b32_e32 v42, 16, v15
	v_cvt_pk_bf16_f32 v80, v12, v13
	v_pk_mul_f32 v[10:11], v[10:11], s[44:45] op_sel_hi:[1,0]
	s_waitcnt vmcnt(7)
	ds_write_b128 v8, v[0:3]
	v_add3_u32 v0, s17, v211, v210
	s_waitcnt vmcnt(6)
	ds_write_b128 v0, v[4:7] offset:17408
	v_add3_u32 v0, s17, v212, v210
	v_add_u32_e32 v8, s38, v180
	v_mad_i64_i32 v[8:9], s[40:41], v8, s0, v[16:17]
	v_lshl_add_u64 v[8:9], v[8:9], 0, s[70:71]
	v_lshl_add_u64 v[8:9], v[8:9], 0, v[48:49]
	s_waitcnt vmcnt(5)
	ds_write_b128 v0, v[18:21]
	v_add3_u32 v0, s17, v213, v210
	s_waitcnt vmcnt(4)
	ds_write_b128 v0, v[22:25] offset:17408
	v_add3_u32 v0, s17, v214, v210
	v_add_u32_e32 v18, s38, v179
	v_mad_i64_i32 v[18:19], s[40:41], v18, s0, v[16:17]
	v_lshl_add_u64 v[18:19], v[18:19], 0, s[70:71]
	s_waitcnt vmcnt(3)
	ds_write_b128 v0, v[26:29]
	v_add3_u32 v0, s17, v215, v210
	s_waitcnt vmcnt(2)
	ds_write_b128 v0, v[30:33] offset:17408
	v_add3_u32 v0, s17, v216, v210
	v_lshl_add_u64 v[18:19], v[18:19], 0, v[48:49]
	s_waitcnt vmcnt(1)
	ds_write_b128 v0, v[34:37]
	v_add3_u32 v0, s17, v217, v210
	v_pk_mul_f32 v[14:15], v[42:43], s[44:45] op_sel_hi:[1,0]
	s_waitcnt vmcnt(0)
	ds_write_b128 v0, v[38:41] offset:17408
	v_add_u32_e32 v0, s38, v185
	v_mad_i64_i32 v[0:1], s[40:41], v0, s0, v[16:17]
	v_lshl_add_u64 v[0:1], v[0:1], 0, s[70:71]
	v_lshl_add_u64 v[0:1], v[0:1], 0, v[48:49]
	v_add_co_u32_e32 v4, vcc, s42, v0
	s_nop 0
	s_nop 0
	v_addc_co_u32_e32 v5, vcc, 0, v1, vcc
	v_add_co_u32_e32 v12, vcc, s42, v8
	s_nop 0
	s_nop 0
	v_addc_co_u32_e32 v13, vcc, 0, v9, vcc
	v_add_co_u32_e32 v18, vcc, s42, v18
	s_nop 1
	v_addc_co_u32_e32 v19, vcc, 0, v19, vcc
	v_cvt_pk_bf16_f32 v78, v10, v11
	v_cvt_pk_bf16_f32 v82, v14, v15
	global_load_dwordx4 v[0:3], v[4:5], off offset:2048
	s_nop 0
	global_load_dwordx4 v[4:7], v[4:5], off offset:3072
	s_nop 0
	global_load_dwordx4 v[8:11], v[12:13], off offset:2048
	s_nop 0
	global_load_dwordx4 v[12:15], v[12:13], off offset:3072
	s_nop 0
	global_load_dwordx4 v[20:23], v[18:19], off offset:2048
	global_load_dwordx4 v[28:31], v[18:19], off offset:3072
	v_add_u32_e32 v18, s38, v178
	v_mad_i64_i32 v[16:17], s[38:39], v18, s0, v[16:17]
	v_lshl_add_u64 v[16:17], v[16:17], 0, s[70:71]
	v_lshl_add_u64 v[16:17], v[16:17], 0, v[48:49]
	v_add_co_u32_e32 v16, vcc, s42, v16
	v_mul_u32_u24_e32 v49, 0x110, v183
	s_nop 0
	v_addc_co_u32_e32 v17, vcc, 0, v17, vcc
	global_load_dwordx4 v[40:43], v[16:17], off offset:2048
	global_load_dwordx4 v[44:47], v[16:17], off offset:3072
	v_add3_u32 v219, s17, v160, v49
	v_add_u32_e32 v49, s23, v178
	v_add_u32_e32 v49, 0xffffc080, v49
	v_perm_b32 v16, v52, v51, s95
	v_mad_i64_i32 v[50:51], s[38:39], v49, s0, 0
	s_and_b32 s38, s36, 0x300
	v_add_u32_e32 v49, s23, v179
	v_readlane_b32 s37, v251, 56
	v_or3_b32 v50, v50, s38, v48
	v_add_u32_e32 v49, 0xffffc080, v49
	v_add3_u32 v218, v84, s37, v83
	v_lshl_add_u64 v[134:135], s[30:31], 0, v[50:51]
	v_mad_i64_i32 v[50:51], s[36:37], v49, s0, 0
	v_add_u32_e32 v49, s23, v180
	v_or3_b32 v50, v50, s38, v48
	v_add_u32_e32 v49, 0xffffc080, v49
	v_lshl_add_u64 v[136:137], s[30:31], 0, v[50:51]
	v_mad_i64_i32 v[50:51], s[36:37], v49, s0, 0
	v_add_u32_e32 v49, s23, v185
	v_or3_b32 v50, v50, s38, v48
	v_add_u32_e32 v49, 0xffffc080, v49
	v_lshl_add_u64 v[138:139], s[30:31], 0, v[50:51]
	v_mad_i64_i32 v[50:51], s[36:37], v49, s0, 0
	v_or3_b32 v50, v50, s38, v48
	v_mov_b32_e32 v48, 0
	v_perm_b32 v19, v58, v57, s95
	v_perm_b32 v18, v56, v55, s95
	v_perm_b32 v17, v54, v53, s95
	v_mov_b32_e32 v27, v65
	v_perm_b32 v26, v64, v63, s95
	v_mov_b32_e32 v25, v61
	v_mov_b32_e32 v24, v60
	v_mov_b32_e32 v35, v74
	v_perm_b32 v34, v67, v68, s95
	v_perm_b32 v33, v69, v70, s95
	v_perm_b32 v32, v71, v72, s95
	v_mov_b32_e32 v39, v82
	v_mov_b32_e32 v38, v80
	v_mov_b32_e32 v37, v78
	v_perm_b32 v36, v75, v76, s95
	v_lshl_add_u64 v[140:141], s[30:31], 0, v[50:51]
	s_mov_b64 s[36:37], 0
	v_mov_b32_e32 v49, v48
	v_mov_b32_e32 v50, v48
	v_mov_b32_e32 v51, v48
	v_mov_b32_e32 v52, v48
	v_mov_b32_e32 v53, v48
	v_mov_b32_e32 v54, v48
	v_mov_b32_e32 v55, v48
	v_mov_b32_e32 v68, v48
	v_mov_b32_e32 v69, v48
	v_mov_b32_e32 v70, v48
	v_mov_b32_e32 v71, v48
	v_mov_b32_e32 v76, v48
	v_mov_b32_e32 v77, v48
	v_mov_b32_e32 v78, v48
	v_mov_b32_e32 v79, v48
	v_mov_b32_e32 v80, v48
	v_mov_b32_e32 v81, v48
	v_mov_b32_e32 v82, v48
	v_mov_b32_e32 v83, v48
	v_mov_b32_e32 v84, v48
	v_mov_b32_e32 v85, v48
	v_mov_b32_e32 v86, v48
	v_mov_b32_e32 v87, v48
	v_mov_b32_e32 v88, v48
	v_mov_b32_e32 v89, v48
	v_mov_b32_e32 v90, v48
	v_mov_b32_e32 v91, v48
	v_mov_b32_e32 v96, v48
	v_mov_b32_e32 v97, v48
	v_mov_b32_e32 v98, v48
	v_mov_b32_e32 v99, v48
	v_mov_b32_e32 v92, v48
	v_mov_b32_e32 v93, v48
	v_mov_b32_e32 v94, v48
	v_mov_b32_e32 v95, v48
	v_mov_b32_e32 v100, v48
	v_mov_b32_e32 v101, v48
	v_mov_b32_e32 v102, v48
	v_mov_b32_e32 v103, v48
	v_mov_b32_e32 v104, v48
	v_mov_b32_e32 v105, v48
	v_mov_b32_e32 v106, v48
	v_mov_b32_e32 v107, v48
	v_mov_b32_e32 v108, v48
	v_mov_b32_e32 v109, v48
	v_mov_b32_e32 v110, v48
	v_mov_b32_e32 v111, v48
	v_mov_b32_e32 v72, v48
	v_mov_b32_e32 v73, v48
	v_mov_b32_e32 v74, v48
	v_mov_b32_e32 v75, v48
	v_mov_b32_e32 v64, v48
	v_mov_b32_e32 v65, v48
	v_mov_b32_e32 v66, v48
	v_mov_b32_e32 v67, v48
	v_mov_b32_e32 v60, v48
	v_mov_b32_e32 v61, v48
	v_mov_b32_e32 v62, v48
	v_mov_b32_e32 v63, v48
	v_mov_b32_e32 v56, v48
	v_mov_b32_e32 v57, v48
	v_mov_b32_e32 v58, v48
	v_mov_b32_e32 v59, v48
	v_mov_b32_e32 v132, v48
	v_mov_b32_e32 v133, v48
	s_waitcnt lgkmcnt(0)
	s_barrier
	s_branch .LBB0_699
.LBB0_698:
	s_mul_i32 s23, s23, 0x8c00
	v_add_u32_e32 v220, s23, v218
	v_add_u32_e32 v113, s23, v219
	ds_read_b128 v[114:117], v113
	ds_read_b128 v[118:121], v113 offset:64
	s_waitcnt lgkmcnt(1)
	v_mfma_f32_16x16x32_bf16 v[114:117], v[114:117], v[16:19], 0
	s_waitcnt lgkmcnt(0)
	v_mfma_f32_16x16x32_bf16 v[144:147], v[118:121], v[24:27], v[114:117]
	ds_read_b128 v[118:121], v113 offset:4416
	s_nop 4
	ds_read_b128 v[114:117], v113 offset:4352
	s_waitcnt lgkmcnt(0)
	v_mfma_f32_16x16x32_bf16 v[114:117], v[114:117], v[16:19], 0
	v_mfma_f32_16x16x32_bf16 v[154:157], v[118:121], v[24:27], v[114:117]
	s_nop 6
	ds_read_b128 v[114:117], v113 offset:8704
	ds_read_b128 v[118:121], v113 offset:8768
	s_waitcnt lgkmcnt(1)
	v_mfma_f32_16x16x32_bf16 v[114:117], v[114:117], v[16:19], 0
	s_waitcnt lgkmcnt(0)
	v_mfma_f32_16x16x32_bf16 v[222:225], v[118:121], v[24:27], v[114:117]
	ds_read_b128 v[118:121], v113 offset:13120
	s_nop 4
	ds_read_b128 v[114:117], v113 offset:13056
	s_waitcnt lgkmcnt(0)
	v_mfma_f32_16x16x32_bf16 v[114:117], v[114:117], v[16:19], 0
	v_mfma_f32_16x16x32_bf16 v[226:229], v[118:121], v[24:27], v[114:117]
	s_nop 6
	ds_read_b128 v[114:117], v113 offset:128
	ds_read_b128 v[118:121], v113 offset:192
	ds_read_b128 v[122:125], v113 offset:4480
	s_waitcnt lgkmcnt(2)
	v_mfma_f32_16x16x32_bf16 v[114:117], v[114:117], v[32:35], 0
	s_waitcnt lgkmcnt(1)
	v_mfma_f32_16x16x32_bf16 v[128:131], v[118:121], v[36:39], v[114:117]
	s_nop 5
	ds_read_b128 v[114:117], v113 offset:4544
	s_waitcnt lgkmcnt(1)
	v_mfma_f32_16x16x32_bf16 v[122:125], v[122:125], v[32:35], 0
	s_waitcnt lgkmcnt(0)
	v_mfma_f32_16x16x32_bf16 v[120:123], v[114:117], v[36:39], v[122:125]
	ds_read_b128 v[114:117], v113 offset:8832
	s_nop 4
	ds_read_b128 v[124:127], v113 offset:8896
	s_waitcnt lgkmcnt(1)
	v_mfma_f32_16x16x32_bf16 v[114:117], v[114:117], v[32:35], 0
	s_waitcnt lgkmcnt(0)
	v_mfma_f32_16x16x32_bf16 v[116:119], v[124:127], v[36:39], v[114:117]
	ds_read_b128 v[124:127], v113 offset:13248
	ds_read_b128 v[172:175], v113 offset:13184
	s_waitcnt lgkmcnt(0)
	v_mfma_f32_16x16x32_bf16 v[172:175], v[172:175], v[32:35], 0
	v_mfma_f32_16x16x32_bf16 v[124:127], v[124:127], v[36:39], v[172:175]
	v_max3_f32 v113, v144, s8, v145
	v_max3_f32 v113, v113, v146, v147
	v_max3_f32 v113, v113, v154, v155
	v_max3_f32 v113, v113, v156, v157
	v_max3_f32 v113, v113, v222, v223
	v_max3_f32 v113, v113, v224, v225
	v_max3_f32 v113, v113, v226, v227
	v_max3_f32 v113, v113, v228, v229
	ds_bpermute_b32 v114, v182, v113
	s_waitcnt lgkmcnt(0)
	v_max_f32_e32 v114, v114, v114
	v_max_f32_e32 v113, v113, v114
	ds_bpermute_b32 v114, v181, v113
	s_waitcnt lgkmcnt(0)
	v_max3_f32 v221, v112, v113, v114
	v_sub_f32_e32 v114, v145, v221
	v_mul_f32_e32 v114, 0x3fb8aa3b, v114
	v_exp_f32_e32 v148, v114
	v_sub_f32_e32 v114, v146, v221
	v_sub_f32_e32 v113, v144, v221
	v_mul_f32_e32 v114, 0x3fb8aa3b, v114
	v_mul_f32_e32 v113, 0x3fb8aa3b, v113
	v_exp_f32_e32 v146, v114
	v_sub_f32_e32 v114, v147, v221
	v_exp_f32_e32 v144, v113
	v_mul_f32_e32 v114, 0x3fb8aa3b, v114
	v_exp_f32_e32 v152, v114
	v_sub_f32_e32 v114, v154, v221
	v_mul_f32_e32 v114, 0x3fb8aa3b, v114
	v_exp_f32_e32 v154, v114
	v_sub_f32_e32 v114, v155, v221
	v_add_f32_e32 v113, 0, v144
	v_mul_f32_e32 v114, 0x3fb8aa3b, v114
	v_add_f32_e32 v113, v148, v113
	v_exp_f32_e32 v158, v114
	v_add_f32_e32 v113, v146, v113
	v_add_f32_e32 v113, v152, v113
	v_add_f32_e32 v113, v154, v113
	v_add_f32_e32 v177, v158, v113
	v_sub_f32_e32 v113, v156, v221
	v_mul_f32_e32 v113, 0x3fb8aa3b, v113
	v_exp_f32_e32 v155, v113
	v_sub_f32_e32 v113, v157, v221
	v_mul_f32_e32 v113, 0x3fb8aa3b, v113
	v_exp_f32_e32 v173, v113
	v_sub_f32_e32 v113, v222, v221
	v_mul_f32_e32 v113, 0x3fb8aa3b, v113
	v_exp_f32_e32 v143, v113
	v_sub_f32_e32 v113, v223, v221
	v_mul_f32_e32 v113, 0x3fb8aa3b, v113
	v_exp_f32_e32 v147, v113
	v_sub_f32_e32 v113, v224, v221
	v_mul_f32_e32 v113, 0x3fb8aa3b, v113
	v_exp_f32_e32 v145, v113
	v_sub_f32_e32 v113, v225, v221
	v_mul_f32_e32 v113, 0x3fb8aa3b, v113
	v_exp_f32_e32 v153, v113
	v_sub_f32_e32 v113, v226, v221
	v_mul_f32_e32 v113, 0x3fb8aa3b, v113
	v_exp_f32_e32 v149, v113
	v_sub_f32_e32 v113, v227, v221
	v_mul_f32_e32 v113, 0x3fb8aa3b, v113
	v_exp_f32_e32 v159, v113
	v_sub_f32_e32 v113, v228, v221
	v_sub_f32_e32 v112, v112, v221
	v_mul_f32_e32 v113, 0x3fb8aa3b, v113
	v_mul_f32_e32 v112, 0x3fb8aa3b, v112
	v_exp_f32_e32 v157, v113
	v_sub_f32_e32 v113, v229, v221
	v_mul_f32_e32 v113, 0x3fb8aa3b, v113
	v_exp_f32_e32 v160, v112
	v_exp_f32_e32 v175, v113
	v_bfe_u32 v176, v144, 16, 1
	v_add3_u32 v231, v144, v176, s94
	v_pk_mul_f32 v[112:113], v[108:109], v[160:161] op_sel_hi:[1,0]
	v_pk_mul_f32 v[108:109], v[104:105], v[160:161] op_sel_hi:[1,0]
	v_pk_mul_f32 v[104:105], v[100:101], v[160:161] op_sel_hi:[1,0]
	v_pk_mul_f32 v[100:101], v[92:93], v[160:161] op_sel_hi:[1,0]
	v_pk_mul_f32 v[92:93], v[96:97], v[160:161] op_sel_hi:[1,0]
	v_max3_f32 v96, v128, s8, v129
	v_max3_f32 v96, v96, v130, v131
	v_max3_f32 v96, v96, v120, v121
	v_max3_f32 v96, v96, v122, v123
	v_max3_f32 v96, v96, v116, v117
	v_max3_f32 v96, v96, v118, v119
	v_max3_f32 v96, v96, v124, v125
	v_cvt_pk_bf16_f32 v237, v155, v173
	v_max3_f32 v96, v96, v126, v127
	v_cvt_pk_bf16_f32 v229, v157, v175
	ds_bpermute_b32 v97, v182, v96
	v_pk_mul_f32 v[114:115], v[110:111], v[160:161] op_sel_hi:[1,0]
	v_pk_mul_f32 v[110:111], v[106:107], v[160:161] op_sel_hi:[1,0]
	v_pk_mul_f32 v[106:107], v[102:103], v[160:161] op_sel_hi:[1,0]
	v_pk_mul_f32 v[102:103], v[94:95], v[160:161] op_sel_hi:[1,0]
	s_waitcnt lgkmcnt(0)
	v_max_f32_e32 v97, v97, v97
	v_max_f32_e32 v96, v96, v97
	ds_bpermute_b32 v97, v181, v96
	v_pk_mul_f32 v[94:95], v[98:99], v[160:161] op_sel_hi:[1,0]
	s_waitcnt lgkmcnt(0)
	v_max3_f32 v222, v142, v96, v97
	v_sub_f32_e32 v98, v129, v222
	v_mul_f32_e32 v98, 0x3fb8aa3b, v98
	v_exp_f32_e32 v129, v98
	v_sub_f32_e32 v98, v130, v222
	v_sub_f32_e32 v97, v128, v222
	v_mul_f32_e32 v98, 0x3fb8aa3b, v98
	v_mul_f32_e32 v97, 0x3fb8aa3b, v97
	v_exp_f32_e32 v130, v98
	v_sub_f32_e32 v98, v131, v222
	v_exp_f32_e32 v128, v97
	v_mul_f32_e32 v98, 0x3fb8aa3b, v98
	v_exp_f32_e32 v131, v98
	v_sub_f32_e32 v98, v120, v222
	v_mul_f32_e32 v98, 0x3fb8aa3b, v98
	v_exp_f32_e32 v239, v98
	v_sub_f32_e32 v98, v121, v222
	v_add_f32_e32 v97, 0, v128
	v_mul_f32_e32 v98, 0x3fb8aa3b, v98
	v_add_f32_e32 v97, v129, v97
	v_exp_f32_e32 v240, v98
	v_add_f32_e32 v97, v130, v97
	v_add_f32_e32 v97, v131, v97
	v_add_f32_e32 v97, v239, v97
	v_add_f32_e32 v176, v240, v97
	v_sub_f32_e32 v97, v122, v222
	v_mul_f32_e32 v97, 0x3fb8aa3b, v97
	v_cvt_pk_bf16_f32 v235, v154, v158
	v_exp_f32_e32 v154, v97
	v_sub_f32_e32 v97, v123, v222
	v_bfe_u32 v172, v146, 16, 1
	v_mul_f32_e32 v97, 0x3fb8aa3b, v97
	v_add3_u32 v233, v146, v172, s94
	v_exp_f32_e32 v172, v97
	v_sub_f32_e32 v97, v116, v222
	v_mul_f32_e32 v97, 0x3fb8aa3b, v97
	v_sub_f32_e32 v96, v142, v222
	v_exp_f32_e32 v142, v97
	v_sub_f32_e32 v97, v117, v222
	v_mul_f32_e32 v97, 0x3fb8aa3b, v97
	v_exp_f32_e32 v146, v97
	v_sub_f32_e32 v97, v118, v222
	v_mul_f32_e32 v97, 0x3fb8aa3b, v97
	v_bfe_u32 v156, v152, 16, 1
	v_cvt_pk_bf16_f32 v226, v145, v153
	v_exp_f32_e32 v144, v97
	v_sub_f32_e32 v97, v119, v222
	v_add3_u32 v234, v152, v156, s94
	v_mul_f32_e32 v97, 0x3fb8aa3b, v97
	v_bfe_u32 v174, v148, 16, 1
	v_exp_f32_e32 v152, v97
	v_sub_f32_e32 v97, v124, v222
	v_add3_u32 v232, v148, v174, s94
	v_mul_f32_e32 v97, 0x3fb8aa3b, v97
	v_cvt_pk_bf16_f32 v224, v143, v147
	v_exp_f32_e32 v148, v97
	v_sub_f32_e32 v97, v125, v222
	v_mul_f32_e32 v97, 0x3fb8aa3b, v97
	v_exp_f32_e32 v158, v97
	v_sub_f32_e32 v97, v126, v222
	v_mul_f32_e32 v97, 0x3fb8aa3b, v97
	v_exp_f32_e32 v156, v97
	v_sub_f32_e32 v97, v127, v222
	v_mul_f32_e32 v96, 0x3fb8aa3b, v96
	v_mul_f32_e32 v97, 0x3fb8aa3b, v97
	v_exp_f32_e32 v174, v97
	v_exp_f32_e32 v120, v96
	v_pk_add_f32 v[96:97], v[154:155], v[176:177]
	v_pk_add_f32 v[96:97], v[172:173], v[96:97]
	v_mov_b32_e32 v121, v160
	v_pk_add_f32 v[96:97], v[142:143], v[96:97]
	v_cvt_pk_bf16_f32 v227, v149, v159
	v_pk_add_f32 v[96:97], v[146:147], v[96:97]
	v_pk_mul_f32 v[98:99], v[70:71], v[120:121] op_sel_hi:[1,0]
	v_pk_add_f32 v[96:97], v[144:145], v[96:97]
	v_pk_mul_f32 v[70:71], v[50:51], v[120:121] op_sel_hi:[1,0]
	v_pk_add_f32 v[96:97], v[152:153], v[96:97]
	v_pk_mul_f32 v[50:51], v[74:75], v[120:121] op_sel_hi:[1,0]
	v_pk_add_f32 v[96:97], v[148:149], v[96:97]
	v_pk_add_f32 v[96:97], v[158:159], v[96:97]
	v_pk_add_f32 v[96:97], v[156:157], v[96:97]
	v_pk_mul_f32 v[118:119], v[78:79], v[120:121] op_sel_hi:[1,0]
	v_pk_add_f32 v[96:97], v[174:175], v[96:97]
	v_pk_mul_f32 v[116:117], v[76:77], v[120:121] op_sel_hi:[1,0]
	v_pk_fma_f32 v[132:133], v[132:133], v[120:121], v[96:97]
	v_pk_mul_f32 v[96:97], v[68:69], v[120:121] op_sel_hi:[1,0]
	v_pk_mul_f32 v[78:79], v[54:55], v[120:121] op_sel_hi:[1,0]
	v_pk_mul_f32 v[76:77], v[52:53], v[120:121] op_sel_hi:[1,0]
	v_pk_mul_f32 v[68:69], v[48:49], v[120:121] op_sel_hi:[1,0]
	v_pk_mul_f32 v[48:49], v[72:73], v[120:121] op_sel_hi:[1,0]
	v_pk_mul_f32 v[54:55], v[66:67], v[120:121] op_sel_hi:[1,0]
	v_pk_mul_f32 v[52:53], v[64:65], v[120:121] op_sel_hi:[1,0]
	v_bfe_u32 v74, v144, 16, 1
	v_bfe_u32 v75, v142, 16, 1
	v_cvt_pk_bf16_f32 v145, v154, v172
	v_cvt_pk_bf16_f32 v153, v128, v129
	v_cvt_pk_bf16_f32 v154, v130, v131
	v_cvt_pk_bf16_f32 v157, v239, v240
	v_bfe_u32 v66, v152, 16, 1
	v_bfe_u32 v67, v146, 16, 1
	v_add3_u32 v240, v142, v75, s94
	v_add3_u32 v241, v144, v74, s94
	v_add_u32_e32 v128, 0x1200, v220
	v_add_u32_e32 v129, 32, v220
	v_add_u32_e32 v130, 0x1220, v220
	v_add_u32_e32 v131, 64, v220
	v_add_u32_e32 v142, 0x1240, v220
	v_add_u32_e32 v144, 0x60, v220
	v_pk_mul_f32 v[90:91], v[90:91], v[160:161] op_sel_hi:[1,0]
	v_pk_mul_f32 v[88:89], v[88:89], v[160:161] op_sel_hi:[1,0]
	v_pk_mul_f32 v[86:87], v[86:87], v[160:161] op_sel_hi:[1,0]
	v_pk_mul_f32 v[84:85], v[84:85], v[160:161] op_sel_hi:[1,0]
	v_pk_mul_f32 v[82:83], v[82:83], v[160:161] op_sel_hi:[1,0]
	v_pk_mul_f32 v[80:81], v[80:81], v[160:161] op_sel_hi:[1,0]
	v_pk_mul_f32 v[62:63], v[62:63], v[120:121] op_sel_hi:[1,0]
	v_pk_mul_f32 v[60:61], v[60:61], v[120:121] op_sel_hi:[1,0]
	v_pk_mul_f32 v[58:59], v[58:59], v[120:121] op_sel_hi:[1,0]
	v_pk_mul_f32 v[56:57], v[56:57], v[120:121] op_sel_hi:[1,0]
	v_add3_u32 v160, v146, v67, s94
	v_add3_u32 v176, v152, v66, s94
	v_cvt_pk_bf16_f32 v242, v148, v158
	v_cvt_pk_bf16_f32 v243, v156, v174
	v_add_u32_e32 v146, 0x1260, v220
	ds_read_b64_tr_b16 v[124:125], v220
	ds_read_b64_tr_b16 v[126:127], v128
	ds_read_b64_tr_b16 v[120:121], v129
	ds_read_b64_tr_b16 v[122:123], v130
	ds_read_b64_tr_b16 v[72:73], v131
	ds_read_b64_tr_b16 v[74:75], v142
	ds_read_b64_tr_b16 v[64:65], v144
	ds_read_b64_tr_b16 v[66:67], v146
	s_waitcnt lgkmcnt(0)
	v_mov_b32_e32 v131, v237
	v_mov_b32_e32 v130, v235
	v_perm_b32 v129, v234, v233, s95
	v_perm_b32 v128, v232, v231, s95
	v_mov_b32_e32 v144, v157
	v_mov_b32_e32 v143, v154
	v_mov_b32_e32 v142, v153
	v_mfma_f32_16x16x32_bf16 v[112:115], v[124:127], v[128:131], v[112:115]
	s_nop 0
	v_mfma_f32_16x16x32_bf16 v[116:119], v[124:127], v[142:145], v[116:119]
	v_mfma_f32_16x16x32_bf16 v[124:127], v[120:123], v[128:131], v[108:111]
	v_mfma_f32_16x16x32_bf16 v[96:99], v[120:123], v[142:145], v[96:99]
	v_mfma_f32_16x16x32_bf16 v[120:123], v[72:75], v[128:131], v[104:107]
	v_mfma_f32_16x16x32_bf16 v[72:75], v[72:75], v[142:145], v[76:79]
	v_mfma_f32_16x16x32_bf16 v[146:149], v[64:67], v[128:131], v[100:103]
	v_mfma_f32_16x16x32_bf16 v[64:67], v[64:67], v[142:145], v[68:71]
	v_add_u32_e32 v108, 0x80, v220
	v_add_u32_e32 v109, 0x1280, v220
	v_add_u32_e32 v110, 0xa0, v220
	v_add_u32_e32 v111, 0x12a0, v220
	v_add_u32_e32 v152, 0xc0, v220
	v_add_u32_e32 v153, 0x12c0, v220
	v_add_u32_e32 v154, 0xe0, v220
	v_add_u32_e32 v155, 0x12e0, v220
	ds_read_b64_tr_b16 v[104:105], v108
	ds_read_b64_tr_b16 v[106:107], v109
	ds_read_b64_tr_b16 v[100:101], v110
	ds_read_b64_tr_b16 v[102:103], v111
	ds_read_b64_tr_b16 v[76:77], v152
	ds_read_b64_tr_b16 v[78:79], v153
	ds_read_b64_tr_b16 v[68:69], v154
	ds_read_b64_tr_b16 v[70:71], v155
	s_waitcnt lgkmcnt(0)
	s_nop 0
	v_mfma_f32_16x16x32_bf16 v[88:91], v[100:103], v[128:131], v[88:91]
	v_mfma_f32_16x16x32_bf16 v[84:87], v[76:79], v[128:131], v[84:87]
	v_mfma_f32_16x16x32_bf16 v[60:63], v[76:79], v[142:145], v[60:63]
	v_mfma_f32_16x16x32_bf16 v[80:83], v[68:71], v[128:131], v[80:83]
	v_mfma_f32_16x16x32_bf16 v[56:59], v[68:71], v[142:145], v[56:59]
	v_mfma_f32_16x16x32_bf16 v[152:155], v[104:107], v[128:131], v[92:95]
	v_mfma_f32_16x16x32_bf16 v[156:159], v[104:107], v[142:145], v[48:51]
	v_mfma_f32_16x16x32_bf16 v[172:175], v[100:103], v[142:145], v[52:55]
	s_nop 0
	v_add_u32_e32 v92, 0x2400, v220
	v_add_u32_e32 v93, 0x3600, v220
	v_add_u32_e32 v94, 0x2420, v220
	v_add_u32_e32 v95, 0x3620, v220
	v_add_u32_e32 v100, 0x2440, v220
	v_add_u32_e32 v101, 0x3640, v220
	v_add_u32_e32 v102, 0x2460, v220
	v_add_u32_e32 v103, 0x3660, v220
	ds_read_b64_tr_b16 v[76:77], v92
	ds_read_b64_tr_b16 v[78:79], v93
	ds_read_b64_tr_b16 v[68:69], v94
	ds_read_b64_tr_b16 v[70:71], v95
	ds_read_b64_tr_b16 v[52:53], v100
	ds_read_b64_tr_b16 v[54:55], v101
	ds_read_b64_tr_b16 v[48:49], v102
	ds_read_b64_tr_b16 v[50:51], v103
	s_waitcnt lgkmcnt(0)
	v_mov_b32_e32 v131, v229
	v_mov_b32_e32 v130, v227
	v_mov_b32_e32 v129, v226
	v_mov_b32_e32 v128, v224
	v_mov_b32_e32 v145, v243
	v_mov_b32_e32 v144, v242
	v_perm_b32 v143, v176, v241, s95
	v_perm_b32 v142, v160, v240, s95
	v_mfma_f32_16x16x32_bf16 v[108:111], v[76:79], v[128:131], v[112:115]
	s_nop 0
	v_mfma_f32_16x16x32_bf16 v[76:79], v[76:79], v[142:145], v[116:119]
	v_mfma_f32_16x16x32_bf16 v[104:107], v[68:71], v[128:131], v[124:127]
	v_mfma_f32_16x16x32_bf16 v[68:71], v[68:71], v[142:145], v[96:99]
	v_mfma_f32_16x16x32_bf16 v[100:103], v[52:55], v[128:131], v[120:123]
	v_mfma_f32_16x16x32_bf16 v[52:55], v[52:55], v[142:145], v[72:75]
	v_mfma_f32_16x16x32_bf16 v[92:95], v[48:51], v[128:131], v[146:149]
	v_mfma_f32_16x16x32_bf16 v[48:51], v[48:51], v[142:145], v[64:67]
	v_add_u32_e32 v96, 0x2480, v220
	v_add_u32_e32 v97, 0x3680, v220
	v_add_u32_e32 v98, 0x24a0, v220
	v_add_u32_e32 v99, 0x36a0, v220
	v_add_u32_e32 v120, 0x24c0, v220
	v_add_u32_e32 v121, 0x36c0, v220
	v_add_u32_e32 v122, 0x24e0, v220
	v_add_u32_e32 v123, 0x36e0, v220
	ds_read_b64_tr_b16 v[72:73], v96
	ds_read_b64_tr_b16 v[74:75], v97
	ds_read_b64_tr_b16 v[64:65], v98
	ds_read_b64_tr_b16 v[66:67], v99
	ds_read_b64_tr_b16 v[116:117], v120
	ds_read_b64_tr_b16 v[118:119], v121
	ds_read_b64_tr_b16 v[112:113], v122
	ds_read_b64_tr_b16 v[114:115], v123
	s_waitcnt lgkmcnt(0)
	s_nop 0
	v_mfma_f32_16x16x32_bf16 v[96:99], v[72:75], v[128:131], v[152:155]
	v_mfma_f32_16x16x32_bf16 v[72:75], v[72:75], v[142:145], v[156:159]
	v_mfma_f32_16x16x32_bf16 v[88:91], v[64:67], v[128:131], v[88:91]
	v_mfma_f32_16x16x32_bf16 v[64:67], v[64:67], v[142:145], v[172:175]
	v_mfma_f32_16x16x32_bf16 v[84:87], v[116:119], v[128:131], v[84:87]
	v_mfma_f32_16x16x32_bf16 v[60:63], v[116:119], v[142:145], v[60:63]
	v_mfma_f32_16x16x32_bf16 v[80:83], v[112:115], v[128:131], v[80:83]
	v_mfma_f32_16x16x32_bf16 v[56:59], v[112:115], v[142:145], v[56:59]
	s_add_u32 s36, s36, 0xd0000
	s_addc_u32 s37, s37, 0
	s_add_i32 s22, s22, 1
	s_cmp_lg_u32 s36, 0x340000
	v_mov_b32_e32 v142, v222
	v_mov_b32_e32 v112, v221
	s_barrier
	s_cbranch_scc0 .LBB0_702

.LBB0_719:
	s_or_b64 exec, exec, s[36:37]
	s_add_i32 s20, s19, 0xfffffe00
	v_ashrrev_i32_e32 v11, 31, v10
	s_lshr_b32 s23, s20, 5
	v_add_u32_e32 v18, -1, v0
	s_lshl_b32 s21, s23, 8
	v_lshl_add_u64 v[10:11], v[10:11], 2, s[26:27]
	v_med3_i32 v19, v18, 0, v201
	global_load_dword v110, v[10:11], off
	v_or_b32_e32 v10, s21, v19
	v_mul_lo_u32 v160, v10, s0
	v_lshl_add_u64 v[104:105], s[6:7], 0, v[160:161]
	s_mov_b64 s[40:41], 0x2400
	v_lshl_add_u64 v[118:119], v[104:105], 0, s[40:41]
	s_lshl_b32 s70, s46, 1
	v_lshl_add_u64 v[10:11], v[118:119], 0, s[70:71]
	global_load_dwordx4 v[10:13], v[10:11], off
	s_mov_b64 s[48:49], 0x2c00
	v_lshl_add_u64 v[116:117], v[104:105], 0, s[48:49]
	v_lshl_add_u64 v[14:15], v[116:117], 0, s[70:71]
	global_load_dwordx4 v[14:17], v[14:15], off
	v_cmp_eq_u32_e64 s[36:37], v18, v19
	v_med3_i32 v18, v0, 0, v201
	v_cmp_eq_u32_e64 s[38:39], v0, v18
	s_or_b32 s20, s46, 8
	s_lshl_b32 s50, s46, 2
	v_mov_b32_e32 v34, s50
	v_lshlrev_b32_e32 v131, 3, v125
	v_lshrrev_b32_e32 v130, 4, v125
	v_and_b32_e32 v129, 15, v0
	s_mov_b32 s52, 0
	v_or_b32_e32 v204, s21, v18
	v_mul_lo_u32 v160, v204, s0
	v_lshl_add_u64 v[106:107], s[6:7], 0, v[160:161]
	v_lshl_add_u64 v[122:123], v[106:107], 0, s[40:41]
	v_lshl_add_u64 v[206:207], v[122:123], 0, s[70:71]
	global_load_dwordx4 v[208:211], v[206:207], off
	v_lshl_add_u64 v[112:113], v[106:107], 0, s[48:49]
	v_lshl_add_u64 v[212:213], v[112:113], 0, s[70:71]
	global_load_dwordx4 v[214:217], v[212:213], off
	v_add_u32_e32 v18, 1, v0
	v_med3_i32 v19, v18, 0, v201
	v_or_b32_e32 v205, s21, v19
	v_mul_lo_u32 v160, v205, s0
	v_lshl_add_u64 v[108:109], s[6:7], 0, v[160:161]
	v_lshl_add_u64 v[120:121], v[108:109], 0, s[40:41]
	v_lshl_add_u64 v[218:219], v[120:121], 0, s[70:71]
	global_load_dwordx4 v[220:223], v[218:219], off
	v_lshl_add_u64 v[114:115], v[108:109], 0, s[48:49]
	v_lshl_add_u64 v[224:225], v[114:115], 0, s[70:71]
	global_load_dwordx4 v[226:229], v[224:225], off
	s_add_u32 s48, s82, s50
	s_addc_u32 s49, s83, 0
	s_add_u32 s46, s48, 0x1000
	s_addc_u32 s47, s49, 0
	global_load_dwordx4 v[230:233], v161, s[46:47] offset:48
	global_load_dwordx4 v[234:237], v161, s[46:47] offset:32
	global_load_dwordx4 v[72:75], v161, s[46:47] offset:16
	global_load_dwordx4 v[80:83], v195, s[48:49]
	global_load_dwordx4 v[238:241], v34, s[82:83] offset:48
	global_load_dwordx4 v[22:25], v34, s[82:83] offset:32
	global_load_dwordx4 v[76:79], v34, s[82:83] offset:16
	global_load_dwordx4 v[84:87], v34, s[82:83]
	global_load_dwordx4 v[26:29], v34, s[80:81] offset:48
	global_load_dwordx4 v[30:33], v34, s[80:81] offset:32
	global_load_dwordx4 v[42:45], v34, s[80:81] offset:16
	global_load_dwordx4 v[46:49], v34, s[80:81]
	s_add_u32 s46, s80, s50
	s_addc_u32 s47, s81, 0
	s_add_u32 s50, s46, 0x1000
	s_addc_u32 s51, s47, 0
	global_load_dwordx4 v[242:245], v161, s[50:51] offset:48
	global_load_dwordx4 v[38:41], v161, s[50:51] offset:32
	global_load_dwordx4 v[50:53], v161, s[50:51] offset:16
	global_load_dwordx4 v[54:57], v195, s[46:47]
	s_add_u32 s50, s46, 0x1800
	s_addc_u32 s51, s47, 0
	global_load_dwordx4 v[144:147], v161, s[50:51] offset:48
	global_load_dwordx4 v[152:155], v161, s[50:51] offset:32
	global_load_dwordx4 v[156:159], v161, s[50:51] offset:16
	global_load_dwordx4 v[92:95], v196, s[46:47] offset:2048
	global_load_dwordx4 v[96:99], v197, s[46:47]
	global_load_dwordx4 v[100:103], v198, s[46:47]
	s_waitcnt vmcnt(27)
	v_cndmask_b32_e64 v61, 0, v10, s[36:37]
	s_nop 0
	s_nop 0
	s_nop 0
	s_nop 0
	v_cndmask_b32_e64 v60, 0, v11, s[36:37]
	s_nop 0
	v_cndmask_b32_e64 v58, 0, v13, s[36:37]
	v_cndmask_b32_e64 v59, 0, v12, s[36:37]
	s_nop 0
	s_nop 0
	s_waitcnt vmcnt(26)
	v_cndmask_b32_e64 v88, 0, v15, s[36:37]
	v_cndmask_b32_e64 v89, 0, v14, s[36:37]
	s_nop 0
	v_cndmask_b32_e64 v70, 0, v17, s[36:37]
	v_cndmask_b32_e64 v71, 0, v16, s[36:37]
	s_nop 0
	s_nop 0
	s_nop 0
	v_lshlrev_b32_e32 v35, 16, v61
	s_waitcnt vmcnt(25)
	v_cndmask_b32_e64 v68, 0, v208, s[38:39]
	s_nop 0
	s_nop 0
	s_nop 0
	s_nop 0
	s_nop 0
	v_cndmask_b32_e64 v66, 0, v209, s[38:39]
	s_waitcnt vmcnt(24)
	v_cndmask_b32_e64 v67, 0, v215, s[38:39]
	v_cndmask_b32_e64 v69, 0, v214, s[38:39]
	s_nop 0
	s_nop 0
	v_cndmask_b32_e64 v62, 0, v211, s[38:39]
	v_cndmask_b32_e64 v64, 0, v210, s[38:39]
	v_cndmask_b32_e64 v63, 0, v217, s[38:39]
	v_cndmask_b32_e64 v65, 0, v216, s[38:39]
	s_nop 0
	s_nop 0
	s_nop 0
	s_nop 0
	s_nop 0
	v_cmp_eq_u32_e64 s[40:41], v18, v19
	s_nop 0
	v_lshlrev_b32_e32 v160, 1, v131
	s_waitcnt vmcnt(23)
	v_cndmask_b32_e64 v132, 0, v223, s[40:41]
	v_cndmask_b32_e64 v134, 0, v222, s[40:41]
	v_cndmask_b32_e64 v136, 0, v221, s[40:41]
	v_cndmask_b32_e64 v138, 0, v220, s[40:41]
	s_waitcnt vmcnt(22)
	v_cndmask_b32_e64 v133, 0, v229, s[40:41]
	v_cndmask_b32_e64 v135, 0, v228, s[40:41]
	v_cndmask_b32_e64 v137, 0, v227, s[40:41]
	v_cndmask_b32_e64 v139, 0, v226, s[40:41]
	s_nop 0
	s_nop 0
	s_nop 0
	s_nop 0
	s_nop 0
	s_nop 0
	s_nop 0
	s_nop 0
	s_nop 0
	s_nop 0
	s_nop 0
	s_nop 0
	s_nop 0
	s_nop 0
	s_nop 0
	s_nop 0
	s_waitcnt vmcnt(10)
	v_fma_f32 v84, v46, v35, v84
	s_nop 0
	s_nop 0
	s_nop 0
	s_nop 0
	v_lshlrev_b32_e32 v46, 16, v89
	s_nop 0
	s_nop 0
	s_waitcnt vmcnt(6)
	v_fma_f32 v143, v54, v46, v80
	v_and_b32_e32 v46, 0xffff0000, v61
	v_fma_f32 v140, v47, v46, v85
	v_and_b32_e32 v46, 0xffff0000, v89
	v_fma_f32 v142, v55, v46, v81
	v_lshlrev_b32_e32 v46, 16, v60
	v_fma_f32 v85, v48, v46, v86
	v_lshlrev_b32_e32 v46, 16, v88
	v_fma_f32 v141, v56, v46, v82
	v_and_b32_e32 v46, 0xffff0000, v60
	v_fmac_f32_e32 v87, v49, v46
	v_and_b32_e32 v46, 0xffff0000, v88
	v_fmac_f32_e32 v83, v57, v46
	v_lshlrev_b32_e32 v46, 16, v59
	v_fma_f32 v80, v42, v46, v76
	v_lshlrev_b32_e32 v42, 16, v71
	v_fma_f32 v86, v50, v42, v72
	v_and_b32_e32 v42, 0xffff0000, v59
	v_fma_f32 v77, v43, v42, v77
	v_and_b32_e32 v42, 0xffff0000, v71
	v_fma_f32 v81, v51, v42, v73
	v_lshlrev_b32_e32 v42, 16, v58
	v_fma_f32 v76, v44, v42, v78
	v_lshlrev_b32_e32 v42, 16, v70
	v_fma_f32 v74, v52, v42, v74
	v_and_b32_e32 v42, 0xffff0000, v58
	v_fmac_f32_e32 v79, v45, v42
	v_and_b32_e32 v42, 0xffff0000, v70
	v_fmac_f32_e32 v75, v53, v42
	s_nop 0
	s_nop 0
	s_nop 0
	global_load_dwordx4 v[70:73], v195, s[46:47] offset:2048
	s_add_u32 s50, s46, 0x2800
	v_lshlrev_b32_e32 v50, 16, v68
	s_addc_u32 s51, s47, 0
	v_and_b32_e32 v68, 0xffff0000, v68
	v_lshlrev_b32_e32 v78, 16, v139
	v_lshl_add_u32 v82, v0, 1, s17
	s_waitcnt vmcnt(0)
	v_fmac_f32_e32 v84, v70, v50
	global_load_dwordx4 v[50:53], v161, s[50:51] offset:48
	global_load_dwordx4 v[58:61], v161, s[50:51] offset:32
	global_load_dwordx4 v[88:91], v161, s[50:51] offset:16
	s_nop 0
	v_fmac_f32_e32 v140, v71, v68
	v_and_b32_e32 v68, 0xffff0000, v69
	s_add_u32 s50, s46, 0x3000
	s_addc_u32 s51, s47, 0
	v_lshlrev_b32_e32 v70, 16, v69
	v_fmac_f32_e32 v142, v93, v68
	v_lshlrev_b32_e32 v68, 16, v66
	v_and_b32_e32 v66, 0xffff0000, v66
	v_fmac_f32_e32 v87, v73, v66
	v_and_b32_e32 v66, 0xffff0000, v67
	v_fmac_f32_e32 v83, v95, v66
	v_lshlrev_b32_e32 v66, 16, v64
	v_fmac_f32_e32 v80, v156, v66
	v_lshlrev_b32_e32 v54, 16, v65
	s_waitcnt vmcnt(0)
	v_fmac_f32_e32 v86, v88, v54
	v_and_b32_e32 v54, 0xffff0000, v64
	v_fmac_f32_e32 v77, v157, v54
	v_and_b32_e32 v54, 0xffff0000, v65
	v_fmac_f32_e32 v81, v89, v54
	v_lshlrev_b32_e32 v54, 16, v62
	v_fmac_f32_e32 v76, v158, v54
	v_lshlrev_b32_e32 v54, 16, v63
	v_fmac_f32_e32 v74, v90, v54
	v_and_b32_e32 v54, 0xffff0000, v62
	v_fmac_f32_e32 v79, v159, v54
	v_and_b32_e32 v54, 0xffff0000, v63
	v_fmac_f32_e32 v75, v91, v54
	global_load_dwordx4 v[54:57], v161, s[50:51] offset:48
	global_load_dwordx4 v[62:65], v161, s[50:51] offset:32
	global_load_dwordx4 v[88:91], v161, s[50:51] offset:16
	s_nop 0
	s_add_u32 s50, s46, 0x4000
	v_fmac_f32_e32 v85, v72, v68
	v_lshlrev_b32_e32 v68, 16, v67
	v_lshlrev_b32_e32 v66, 16, v138
	s_addc_u32 s51, s47, 0
	v_fmac_f32_e32 v143, v92, v70
	v_fmac_f32_e32 v141, v94, v68
	v_fmac_f32_e32 v84, v96, v66
	global_load_dwordx4 v[66:69], v161, s[50:51] offset:48
	global_load_dwordx4 v[70:73], v161, s[50:51] offset:32
	global_load_dwordx4 v[92:95], v161, s[50:51] offset:16
	s_nop 0
	s_lshl_b32 s50, s20, 1
	s_mov_b32 s51, s71
	v_fmac_f32_e32 v143, v100, v78
	v_and_b32_e32 v78, 0xffff0000, v138
	v_fmac_f32_e32 v140, v97, v78
	v_and_b32_e32 v78, 0xffff0000, v139
	v_fmac_f32_e32 v142, v101, v78
	v_lshlrev_b32_e32 v78, 16, v136
	v_fmac_f32_e32 v85, v98, v78
	v_lshlrev_b32_e32 v78, 16, v137
	v_fmac_f32_e32 v141, v102, v78
	v_and_b32_e32 v78, 0xffff0000, v136
	v_fmac_f32_e32 v87, v99, v78
	v_and_b32_e32 v78, 0xffff0000, v137
	v_fmac_f32_e32 v83, v103, v78
	v_lshlrev_b32_e32 v78, 16, v134
	s_waitcnt vmcnt(3)
	v_fmac_f32_e32 v80, v88, v78
	v_lshlrev_b32_e32 v78, 16, v135
	s_waitcnt vmcnt(0)
	v_fmac_f32_e32 v86, v92, v78
	v_and_b32_e32 v78, 0xffff0000, v134
	v_fmac_f32_e32 v77, v89, v78
	v_and_b32_e32 v78, 0xffff0000, v135
	v_fmac_f32_e32 v81, v93, v78
	v_lshlrev_b32_e32 v78, 16, v132
	v_fmac_f32_e32 v76, v90, v78
	v_lshlrev_b32_e32 v78, 16, v133
	v_fmac_f32_e32 v74, v94, v78
	v_and_b32_e32 v78, 0xffff0000, v132
	v_fmac_f32_e32 v79, v91, v78
	v_and_b32_e32 v78, 0xffff0000, v133
	v_fmac_f32_e32 v75, v95, v78
	v_bfe_u32 v78, v143, 16, 1
	v_add3_u32 v78, v143, v78, s94
	ds_write_b16_d16_hi v82, v78 offset:512
	v_bfe_u32 v78, v84, 16, 1
	v_add3_u32 v78, v84, v78, s94
	ds_write_b16_d16_hi v82, v78 offset:24576
	v_bfe_u32 v78, v142, 16, 1
	v_add3_u32 v78, v142, v78, s94
	ds_write_b16_d16_hi v82, v78 offset:2048
	v_bfe_u32 v78, v140, 16, 1
	v_add3_u32 v78, v140, v78, s94
	ds_write_b16_d16_hi v82, v78 offset:25088
	v_bfe_u32 v78, v141, 16, 1
	v_add3_u32 v78, v141, v78, s94
	ds_write_b16_d16_hi v82, v78 offset:3584
	v_bfe_u32 v78, v85, 16, 1
	v_add3_u32 v78, v85, v78, s94
	ds_write_b16_d16_hi v82, v78 offset:25600
	v_bfe_u32 v78, v83, 16, 1
	v_add3_u32 v78, v83, v78, s94
	ds_write_b16_d16_hi v82, v78 offset:5120
	v_bfe_u32 v78, v87, 16, 1
	v_add3_u32 v78, v87, v78, s94
	ds_write_b16_d16_hi v82, v78 offset:26112
	v_bfe_u32 v78, v86, 16, 1
	v_add3_u32 v78, v86, v78, s94
	ds_write_b16_d16_hi v82, v78 offset:6656
	v_bfe_u32 v78, v80, 16, 1
	v_add3_u32 v78, v80, v78, s94
	ds_write_b16_d16_hi v82, v78 offset:26624
	v_bfe_u32 v78, v81, 16, 1
	v_add3_u32 v78, v81, v78, s94
	ds_write_b16_d16_hi v82, v78 offset:8192
	v_bfe_u32 v78, v77, 16, 1
	v_add3_u32 v77, v77, v78, s94
	ds_write_b16_d16_hi v82, v77 offset:27136
	v_bfe_u32 v77, v74, 16, 1
	v_add3_u32 v74, v74, v77, s94
	ds_write_b16_d16_hi v82, v74 offset:9728
	v_bfe_u32 v74, v76, 16, 1
	v_add3_u32 v74, v76, v74, s94
	ds_write_b16_d16_hi v82, v74 offset:27648
	v_bfe_u32 v74, v75, 16, 1
	v_add3_u32 v74, v75, v74, s94
	ds_write_b16_d16_hi v82, v74 offset:11264
	v_bfe_u32 v74, v79, 16, 1
	v_add3_u32 v74, v79, v74, s94
	ds_write_b16_d16_hi v82, v74 offset:28160
	v_lshl_add_u64 v[74:75], v[118:119], 0, s[50:51]
	global_load_dwordx4 v[74:77], v[74:75], off
	v_lshl_add_u64 v[78:79], v[116:117], 0, s[50:51]
	global_load_dwordx4 v[78:81], v[78:79], off
	s_waitcnt vmcnt(1)
	v_cndmask_b32_e64 v85, 0, v75, s[36:37]
	v_cndmask_b32_e64 v86, 0, v74, s[36:37]
	v_lshl_add_u64 v[74:75], v[122:123], 0, s[50:51]
	v_cndmask_b32_e64 v83, 0, v77, s[36:37]
	v_cndmask_b32_e64 v84, 0, v76, s[36:37]
	s_waitcnt vmcnt(0)
	v_cndmask_b32_e64 v89, 0, v79, s[36:37]
	v_cndmask_b32_e64 v90, 0, v78, s[36:37]
	global_load_dwordx4 v[74:77], v[74:75], off
	v_lshl_add_u64 v[78:79], v[112:113], 0, s[50:51]
	v_cndmask_b32_e64 v87, 0, v81, s[36:37]
	v_cndmask_b32_e64 v88, 0, v80, s[36:37]
	global_load_dwordx4 v[78:81], v[78:79], off
	v_lshlrev_b32_e32 v99, 16, v86
	v_fma_f32 v22, v30, v99, v22
	v_lshlrev_b32_e32 v30, 16, v90
	v_fma_f32 v18, v38, v30, v234
	v_and_b32_e32 v30, 0xffff0000, v86
	v_fma_f32 v23, v31, v30, v23
	v_and_b32_e32 v30, 0xffff0000, v90
	v_fma_f32 v19, v39, v30, v235
	v_lshlrev_b32_e32 v30, 16, v85
	v_fma_f32 v24, v32, v30, v24
	v_lshlrev_b32_e32 v30, 16, v89
	v_fma_f32 v20, v40, v30, v236
	v_and_b32_e32 v30, 0xffff0000, v85
	v_fmac_f32_e32 v25, v33, v30
	v_and_b32_e32 v30, 0xffff0000, v89
	v_fmac_f32_e32 v237, v41, v30
	v_lshlrev_b32_e32 v30, 16, v84
	v_fma_f32 v14, v26, v30, v238
	v_lshlrev_b32_e32 v26, 16, v88
	v_fma_f32 v10, v242, v26, v230
	v_and_b32_e32 v26, 0xffff0000, v84
	v_fma_f32 v15, v27, v26, v239
	v_and_b32_e32 v26, 0xffff0000, v88
	v_fma_f32 v11, v243, v26, v231
	v_lshlrev_b32_e32 v26, 16, v83
	v_fma_f32 v16, v28, v26, v240
	v_lshlrev_b32_e32 v26, 16, v87
	v_fma_f32 v12, v244, v26, v232
	v_and_b32_e32 v26, 0xffff0000, v83
	v_fmac_f32_e32 v241, v29, v26
	v_and_b32_e32 v26, 0xffff0000, v87
	v_fmac_f32_e32 v233, v245, v26
	v_or_b32_e32 v39, v128, v127
	v_or_b32_e32 v40, 0x8000, v39
	s_waitcnt vmcnt(1)
	v_cndmask_b32_e64 v93, 0, v75, s[38:39]
	v_cndmask_b32_e64 v94, 0, v74, s[38:39]
	v_lshl_add_u64 v[74:75], v[120:121], 0, s[50:51]
	v_cndmask_b32_e64 v91, 0, v77, s[38:39]
	v_cndmask_b32_e64 v92, 0, v76, s[38:39]
	s_waitcnt vmcnt(0)
	v_cndmask_b32_e64 v97, 0, v79, s[38:39]
	v_cndmask_b32_e64 v98, 0, v78, s[38:39]
	global_load_dwordx4 v[74:77], v[74:75], off
	v_lshl_add_u64 v[78:79], v[114:115], 0, s[50:51]
	v_cndmask_b32_e64 v95, 0, v81, s[38:39]
	v_cndmask_b32_e64 v96, 0, v80, s[38:39]
	global_load_dwordx4 v[78:81], v[78:79], off
	v_lshlrev_b32_e32 v26, 16, v94
	v_fmac_f32_e32 v22, v152, v26
	v_lshlrev_b32_e32 v26, 16, v98
	v_fmac_f32_e32 v18, v58, v26
	v_and_b32_e32 v26, 0xffff0000, v94
	v_fmac_f32_e32 v23, v153, v26
	v_and_b32_e32 v26, 0xffff0000, v98
	v_fmac_f32_e32 v19, v59, v26
	v_lshlrev_b32_e32 v26, 16, v93
	v_fmac_f32_e32 v24, v154, v26
	v_lshlrev_b32_e32 v26, 16, v97
	v_fmac_f32_e32 v20, v60, v26
	v_and_b32_e32 v26, 0xffff0000, v93
	v_fmac_f32_e32 v25, v155, v26
	v_and_b32_e32 v26, 0xffff0000, v97
	v_fmac_f32_e32 v237, v61, v26
	v_lshlrev_b32_e32 v26, 16, v92
	v_fmac_f32_e32 v14, v144, v26
	v_lshlrev_b32_e32 v26, 16, v96
	v_fmac_f32_e32 v10, v50, v26
	v_and_b32_e32 v26, 0xffff0000, v92
	v_fmac_f32_e32 v15, v145, v26
	v_and_b32_e32 v26, 0xffff0000, v96
	v_fmac_f32_e32 v11, v51, v26
	v_lshlrev_b32_e32 v26, 16, v91
	v_fmac_f32_e32 v16, v146, v26
	v_lshlrev_b32_e32 v26, 16, v95
	v_fmac_f32_e32 v12, v52, v26
	v_and_b32_e32 v26, 0xffff0000, v91
	v_fmac_f32_e32 v241, v147, v26
	v_and_b32_e32 v26, 0xffff0000, v95
	v_fmac_f32_e32 v233, v53, v26
	v_readlane_b32 s50, v253, 32
	v_readlane_b32 s51, v253, 33
	s_waitcnt vmcnt(1)
	v_cndmask_b32_e64 v74, 0, v74, s[40:41]
	v_lshlrev_b32_e32 v26, 16, v74
	v_fmac_f32_e32 v22, v62, v26
	v_cndmask_b32_e64 v75, 0, v75, s[40:41]
	s_waitcnt vmcnt(0)
	v_cndmask_b32_e64 v78, 0, v78, s[40:41]
	v_lshlrev_b32_e32 v26, 16, v78
	v_fmac_f32_e32 v18, v70, v26
	v_and_b32_e32 v26, 0xffff0000, v74
	v_fmac_f32_e32 v23, v63, v26
	v_and_b32_e32 v26, 0xffff0000, v78
	v_cndmask_b32_e64 v79, 0, v79, s[40:41]
	v_fmac_f32_e32 v19, v71, v26
	v_lshlrev_b32_e32 v26, 16, v75
	v_fmac_f32_e32 v24, v64, v26
	v_lshlrev_b32_e32 v26, 16, v79
	v_fmac_f32_e32 v20, v72, v26
	v_and_b32_e32 v26, 0xffff0000, v75
	v_cndmask_b32_e64 v76, 0, v76, s[40:41]
	v_fmac_f32_e32 v25, v65, v26
	v_and_b32_e32 v26, 0xffff0000, v79
	v_cndmask_b32_e64 v80, 0, v80, s[40:41]
	v_fmac_f32_e32 v237, v73, v26
	v_lshlrev_b32_e32 v26, 16, v76
	v_fmac_f32_e32 v14, v54, v26
	v_lshlrev_b32_e32 v26, 16, v80
	v_fmac_f32_e32 v10, v66, v26
	v_and_b32_e32 v26, 0xffff0000, v76
	v_cndmask_b32_e64 v77, 0, v77, s[40:41]
	v_fmac_f32_e32 v15, v55, v26
	v_and_b32_e32 v26, 0xffff0000, v80
	v_cndmask_b32_e64 v81, 0, v81, s[40:41]
	v_fmac_f32_e32 v11, v67, v26
	v_lshlrev_b32_e32 v26, 16, v77
	v_fmac_f32_e32 v16, v56, v26
	v_lshlrev_b32_e32 v26, 16, v81
	v_fmac_f32_e32 v12, v68, v26
	v_and_b32_e32 v26, 0xffff0000, v77
	v_fmac_f32_e32 v241, v57, v26
	v_and_b32_e32 v26, 0xffff0000, v81
	v_fmac_f32_e32 v233, v69, v26
	v_bfe_u32 v26, v18, 16, 1
	v_add3_u32 v18, v18, v26, s94
	ds_write_b16_d16_hi v82, v18 offset:12800
	v_bfe_u32 v18, v22, 16, 1
	v_add3_u32 v18, v22, v18, s94
	ds_write_b16_d16_hi v82, v18 offset:28672
	v_bfe_u32 v18, v19, 16, 1
	v_add3_u32 v18, v19, v18, s94
	ds_write_b16_d16_hi v82, v18 offset:14336
	v_bfe_u32 v18, v23, 16, 1
	v_add3_u32 v18, v23, v18, s94
	ds_write_b16_d16_hi v82, v18 offset:29184
	v_bfe_u32 v18, v20, 16, 1
	v_add3_u32 v18, v20, v18, s94
	ds_write_b16_d16_hi v82, v18 offset:15872
	v_bfe_u32 v18, v24, 16, 1
	v_add3_u32 v18, v24, v18, s94
	ds_write_b16_d16_hi v82, v18 offset:29696
	v_bfe_u32 v18, v237, 16, 1
	v_add3_u32 v18, v237, v18, s94
	ds_write_b16_d16_hi v82, v18 offset:17408
	v_bfe_u32 v18, v25, 16, 1
	v_add3_u32 v18, v25, v18, s94
	ds_write_b16_d16_hi v82, v18 offset:30208
	v_bfe_u32 v18, v10, 16, 1
	v_add3_u32 v10, v10, v18, s94
	ds_write_b16_d16_hi v82, v10 offset:18944
	v_bfe_u32 v10, v14, 16, 1
	v_add3_u32 v10, v14, v10, s94
	ds_write_b16_d16_hi v82, v10 offset:30720
	v_bfe_u32 v10, v11, 16, 1
	v_add3_u32 v10, v11, v10, s94
	ds_write_b16_d16_hi v82, v10 offset:20480
	v_bfe_u32 v10, v15, 16, 1
	v_add3_u32 v10, v15, v10, s94
	ds_write_b16_d16_hi v82, v10 offset:31232
	v_bfe_u32 v10, v12, 16, 1
	v_add3_u32 v10, v12, v10, s94
	ds_write_b16_d16_hi v82, v10 offset:22016
	v_bfe_u32 v10, v16, 16, 1
	v_add3_u32 v10, v16, v10, s94
	ds_write_b16_d16_hi v82, v10 offset:31744
	v_bfe_u32 v10, v233, 16, 1
	v_add3_u32 v10, v233, v10, s94
	ds_write_b16_d16_hi v82, v10 offset:23552
	v_bfe_u32 v10, v241, 16, 1
	v_add3_u32 v10, v241, v10, s94
	ds_write_b16_d16_hi v82, v10 offset:32256
	v_mbcnt_hi_u32_b32 v10, -1, v194
	v_and_b32_e32 v11, 64, v10
	v_add_u32_e32 v11, 64, v11
	v_xor_b32_e32 v12, 32, v10
	v_cmp_lt_i32_e32 vcc, v12, v11
	v_lshl_add_u64 v[22:23], s[50:51], 0, v[160:161]
	s_movk_i32 s50, 0x600
	v_cndmask_b32_e32 v12, v10, v12, vcc
	v_lshlrev_b32_e32 v29, 2, v12
	v_xor_b32_e32 v12, 16, v10
	v_cmp_lt_i32_e32 vcc, v12, v11
	v_add_u32_e32 v25, s17, v126
	v_add_u32_e32 v28, v25, v160
	v_cndmask_b32_e32 v12, v10, v12, vcc
	v_lshlrev_b32_e32 v30, 2, v12
	v_xor_b32_e32 v12, 8, v10
	v_cmp_lt_i32_e32 vcc, v12, v11
	s_waitcnt lgkmcnt(0)
	v_mov_b32_e32 v13, v233
	v_mov_b32_e32 v17, v241
	v_mov_b32_e32 v21, v237
	v_mov_b32_e32 v34, v242
	v_mov_b32_e32 v35, v243
	v_mov_b32_e32 v36, v244
	v_mov_b32_e32 v37, v245
	v_mov_b32_e32 v42, v144
	v_mov_b32_e32 v43, v145
	v_mov_b32_e32 v44, v146
	v_mov_b32_e32 v45, v147
	v_mov_b32_e32 v46, v152
	v_mov_b32_e32 v47, v153
	v_mov_b32_e32 v48, v154
	v_mov_b32_e32 v49, v155
	s_barrier
	v_cndmask_b32_e32 v12, v10, v12, vcc
	v_lshlrev_b32_e32 v31, 2, v12
	v_xor_b32_e32 v12, 4, v10
	v_cmp_lt_i32_e32 vcc, v12, v11
	s_nop 1
	v_cndmask_b32_e32 v12, v10, v12, vcc
	v_lshlrev_b32_e32 v32, 2, v12
	v_xor_b32_e32 v12, 2, v10
	v_cmp_lt_i32_e32 vcc, v12, v11
	s_nop 1
	v_cndmask_b32_e32 v12, v10, v12, vcc
	v_lshlrev_b32_e32 v33, 2, v12
	v_xor_b32_e32 v12, 1, v10
	v_cmp_lt_i32_e32 vcc, v12, v11
	s_nop 1
	v_cndmask_b32_e32 v10, v10, v12, vcc
	v_lshlrev_b32_e32 v34, 2, v10
	v_lshlrev_b32_e32 v10, 3, v130
	v_sub_u32_e32 v35, v10, v129
	v_lshlrev_b32_e32 v10, 4, v129
	v_lshlrev_b32_e32 v11, 1, v35
	v_lshl_or_b32 v37, v130, 2, v10
	v_mul_lo_u32 v10, v1, s50
	v_and_b32_e32 v36, 2, v11
	v_lshl_or_b32 v10, v129, 5, v10
	v_and_b32_e32 v11, 48, v125
	v_lshl_add_u32 v38, v37, 1, s17
	v_add3_u32 v41, v10, v11, s17

.LBB0_751:
	s_andn2_b64 vcc, exec, s[36:37]
	s_cbranch_vccnz .LBB0_774
	v_mov_b32_e32 v56, v189
	v_readlane_b32 s36, v251, 47
	v_and_b32_e32 v0, 63, v56
	v_lshlrev_b32_e32 v0, 2, v0
	v_readlane_b32 s37, v251, 48
	s_nop 4
	global_load_dword v16, v0, s[36:37]
	global_load_dword v17, v0, s[36:37] offset:256
	global_load_dword v18, v0, s[36:37] offset:512
	global_load_dword v19, v0, s[36:37] offset:768
	s_add_i32 s20, s19, 0xffffff00
	s_lshr_b32 s38, s20, 6
	s_lshl_b32 s20, s19, 6
	s_lshl_b32 s23, s38, 10
	s_and_b32 s20, s20, 0x3c0
	s_or_b32 s20, s23, s20
	v_ashrrev_i32_e32 v0, 2, v56
	s_addk_i32 s20, 0x1000
	v_and_b32_e32 v206, -16, v0
	v_and_b32_e32 v204, 15, v56
	v_add_u32_e32 v0, s20, v206
	s_lshl_b32 s21, s19, 3
	v_or_b32_e32 v2, v0, v204
	v_mov_b64_e32 v[0:1], s[6:7]
	s_and_b32 s21, s21, 0x180
	v_mad_i64_i32 v[0:1], s[36:37], v2, s0, v[0:1]
	s_lshl_b32 s36, s21, 1
	s_mov_b32 s37, s71
	v_lshl_add_u64 v[0:1], v[0:1], 0, s[36:37]
	v_and_b32_e32 v160, 48, v56
	v_lshl_add_u64 v[4:5], v[0:1], 0, v[160:161]
	s_movk_i32 s22, 0x1000
	v_add_co_u32_e32 v0, vcc, s22, v4
	v_mbcnt_hi_u32_b32 v151, -1, v194
	s_nop 0
	v_addc_co_u32_e32 v1, vcc, 0, v5, vcc
	global_load_dwordx4 v[0:3], v[0:1], off offset:1024
	v_and_b32_e32 v8, 64, v151
	s_mov_b64 s[36:37], 0x1400
	v_xor_b32_e32 v9, 32, v151
	v_add_u32_e32 v208, 64, v8
	v_lshl_add_u64 v[12:13], v[4:5], 0, s[36:37]
	v_xor_b32_e32 v10, 16, v151
	v_cmp_lt_i32_e32 vcc, v9, v208
	global_load_dwordx4 v[4:7], v[12:13], off offset:64
	v_xor_b32_e32 v11, 8, v151
	v_cndmask_b32_e32 v8, v151, v9, vcc
	v_cmp_lt_i32_e32 vcc, v10, v208
	v_lshlrev_b32_e32 v141, 2, v8
	v_xor_b32_e32 v14, 4, v151
	v_cndmask_b32_e32 v9, v151, v10, vcc
	v_cmp_lt_i32_e32 vcc, v11, v208
	v_lshlrev_b32_e32 v205, 2, v9
	s_mov_b32 s40, 0x3e000000
	v_cndmask_b32_e32 v10, v151, v11, vcc
	v_lshlrev_b32_e32 v22, 2, v10
	global_load_dwordx4 v[8:11], v[12:13], off offset:128
	v_cmp_lt_i32_e32 vcc, v14, v208
	v_xor_b32_e32 v15, 2, v151
	s_lshl_b32 s36, s38, 19
	v_cndmask_b32_e32 v14, v151, v14, vcc
	v_lshlrev_b32_e32 v25, 2, v14
	v_cmp_lt_i32_e32 vcc, v15, v208
	v_readlane_b32 s37, v251, 42
	v_ashrrev_i32_e32 v138, 4, v56
	v_cndmask_b32_e32 v15, v151, v15, vcc
	v_lshlrev_b32_e32 v26, 2, v15
	global_load_dwordx4 v[12:15], v[12:13], off offset:192
	s_or_b32 s36, s36, s37
	v_ashrrev_i32_e32 v139, 31, v138
	s_or_b32 s70, s36, s21
	v_lshlrev_b64 v[42:43], 9, v[138:139]
	v_lshlrev_b32_e32 v140, 3, v204
	v_readlane_b32 s36, v252, 55
	v_readlane_b32 s38, v252, 57
	v_readlane_b32 s37, v252, 56
	v_readlane_b32 s39, v252, 58
	v_or_b32_e32 v44, s70, v140
	v_mov_b32_e32 v45, v161
	s_barrier
	v_lshlrev_b32_e32 v207, 3, v56
	s_mov_b32 s22, 0
	v_mov_b32_e32 v154, 0xf149f2ca
	s_waitcnt vmcnt(0)
	v_mul_f32_e32 v20, v16, v17
	ds_bpermute_b32 v23, v141, v20
	s_waitcnt vmcnt(4)
	v_mul_f32_e32 v21, v18, v19
	ds_bpermute_b32 v24, v141, v21
	v_mov_b32_e32 v112, 0xf149f2ca
	s_mov_b64 s[42:43], 0x1800
	s_waitcnt lgkmcnt(1)
	v_fmac_f32_e32 v23, v16, v17
	ds_bpermute_b32 v27, v205, v23
	s_waitcnt lgkmcnt(1)
	v_fmac_f32_e32 v24, v18, v19
	ds_bpermute_b32 v28, v205, v24
	s_mov_b64 s[44:45], 0x1c00
	s_mov_b64 s[46:47], 0xf7c0000
	s_waitcnt lgkmcnt(1)
	v_add_f32_e32 v23, v23, v27
	ds_bpermute_b32 v27, v22, v23
	s_waitcnt lgkmcnt(1)
	v_add_f32_e32 v24, v24, v28
	ds_bpermute_b32 v22, v22, v24
	s_mov_b64 s[48:49], 0xfbc0000
	s_waitcnt lgkmcnt(0)
	v_add_f32_e32 v22, v24, v22
	ds_bpermute_b32 v24, v25, v22
	s_waitcnt lgkmcnt(0)
	v_add_f32_e32 v212, v22, v24
	ds_bpermute_b32 v213, v26, v212
	s_waitcnt vmcnt(3)
	v_and_b32_e32 v17, 0xffff0000, v0
	v_lshlrev_b32_e32 v16, 16, v0
	v_and_b32_e32 v19, 0xffff0000, v1
	v_lshlrev_b32_e32 v18, 16, v1
	v_and_b32_e32 v1, 0xffff0000, v2
	v_lshlrev_b32_e32 v0, 16, v2
	v_and_b32_e32 v21, 0xffff0000, v3
	v_lshlrev_b32_e32 v20, 16, v3
	v_pk_mul_f32 v[2:3], v[16:17], s[40:41] op_sel_hi:[1,0]
	v_pk_mul_f32 v[0:1], v[0:1], s[40:41] op_sel_hi:[1,0]
	v_bfe_u32 v33, v2, 16, 1
	v_add3_u32 v57, v2, v33, s94
	v_add_f32_e32 v2, v23, v27
	ds_bpermute_b32 v23, v25, v2
	v_cvt_pk_bf16_f32 v62, v0, v1
	s_waitcnt vmcnt(2)
	v_and_b32_e32 v1, 0xffff0000, v4
	v_lshlrev_b32_e32 v0, 16, v4
	v_pk_mul_f32 v[0:1], v[0:1], s[40:41] op_sel_hi:[1,0]
	v_pk_mul_f32 v[16:17], v[18:19], s[40:41] op_sel_hi:[1,0]
	s_waitcnt lgkmcnt(0)
	v_add_f32_e32 v210, v2, v23
	v_cvt_pk_bf16_f32 v74, v0, v1
	s_waitcnt vmcnt(1)
	v_and_b32_e32 v1, 0xffff0000, v8
	v_lshlrev_b32_e32 v0, 16, v8
	v_bfe_u32 v28, v3, 16, 1
	v_cvt_pk_bf16_f32 v60, v16, v17
	v_and_b32_e32 v17, 0xffff0000, v7
	v_lshlrev_b32_e32 v16, 16, v7
	v_pk_mul_f32 v[40:41], v[0:1], s[40:41] op_sel_hi:[1,0]
	v_and_b32_e32 v1, 0xffff0000, v9
	v_lshlrev_b32_e32 v0, 16, v9
	v_and_b32_e32 v37, 0xffff0000, v10
	v_lshlrev_b32_e32 v36, 16, v10
	v_add_u32_e32 v10, 0x100, v56
	v_pk_mul_f32 v[18:19], v[20:21], s[40:41] op_sel_hi:[1,0]
	v_add3_u32 v58, v3, v28, s94
	v_and_b32_e32 v3, 0xffff0000, v5
	v_lshlrev_b32_e32 v2, 16, v5
	v_and_b32_e32 v5, 0xffff0000, v6
	v_lshlrev_b32_e32 v4, 16, v6
	v_pk_mul_f32 v[6:7], v[16:17], s[40:41] op_sel_hi:[1,0]
	v_pk_mul_f32 v[8:9], v[0:1], s[40:41] op_sel_hi:[1,0]
	v_lshl_add_u64 v[0:1], v[42:43], 0, s[70:71]
	v_ashrrev_i32_e32 v136, 4, v10
	v_pk_mul_f32 v[2:3], v[2:3], s[40:41] op_sel_hi:[1,0]
	v_pk_mul_f32 v[4:5], v[4:5], s[40:41] op_sel_hi:[1,0]
	v_or_b32_e32 v0, v0, v140
	v_ashrrev_i32_e32 v137, 31, v136
	v_add_u32_e32 v10, 0x200, v56
	v_cvt_pk_bf16_f32 v72, v18, v19
	v_cvt_pk_bf16_f32 v80, v6, v7
	v_lshlrev_b64 v[0:1], 1, v[0:1]
	v_lshlrev_b64 v[16:17], 9, v[136:137]
	v_ashrrev_i32_e32 v134, 4, v10
	v_add_u32_e32 v10, 0x300, v56
	v_cvt_pk_bf16_f32 v76, v2, v3
	v_cvt_pk_bf16_f32 v78, v4, v5
	v_lshl_add_u64 v[2:3], s[36:37], 0, v[0:1]
	v_lshl_add_u64 v[4:5], s[38:39], 0, v[0:1]
	v_lshl_add_u64 v[16:17], v[16:17], 0, v[44:45]
	v_ashrrev_i32_e32 v135, 31, v134
	v_ashrrev_i32_e32 v132, 4, v10
	global_load_dwordx4 v[0:3], v[2:3], off
	s_nop 0
	global_load_dwordx4 v[4:7], v[4:5], off
	v_lshlrev_b64 v[46:47], 1, v[16:17]
	v_lshlrev_b64 v[24:25], 9, v[134:135]
	v_ashrrev_i32_e32 v133, 31, v132
	v_lshl_add_u64 v[16:17], s[36:37], 0, v[46:47]
	v_lshl_add_u64 v[20:21], s[38:39], 0, v[46:47]
	v_lshl_add_u64 v[24:25], v[24:25], 0, v[44:45]
	v_lshlrev_b64 v[32:33], 9, v[132:133]
	global_load_dwordx4 v[16:19], v[16:17], off
	s_nop 0
	global_load_dwordx4 v[20:23], v[20:21], off
	v_lshlrev_b64 v[48:49], 1, v[24:25]
	v_lshl_add_u64 v[32:33], v[32:33], 0, v[44:45]
	v_lshl_add_u64 v[24:25], s[36:37], 0, v[48:49]
	v_lshl_add_u64 v[28:29], s[38:39], 0, v[48:49]
	v_lshlrev_b64 v[50:51], 1, v[32:33]
	ds_bpermute_b32 v211, v26, v210
	global_load_dwordx4 v[24:27], v[24:25], off
	s_nop 0
	global_load_dwordx4 v[28:31], v[28:29], off
	v_lshl_add_u64 v[32:33], s[36:37], 0, v[50:51]
	global_load_dwordx4 v[32:35], v[32:33], off
	v_pk_mul_f32 v[52:53], v[36:37], s[40:41] op_sel_hi:[1,0]
	v_lshl_add_u64 v[36:37], s[38:39], 0, v[50:51]
	global_load_dwordx4 v[36:39], v[36:37], off
	v_and_b32_e32 v55, 0xffff0000, v11
	v_lshlrev_b32_e32 v54, 16, v11
	v_pk_mul_f32 v[10:11], v[54:55], s[40:41] op_sel_hi:[1,0]
	v_bfe_u32 v54, v11, 16, 1
	v_bfe_u32 v55, v10, 16, 1
	v_add3_u32 v55, v10, v55, s94
	v_add3_u32 v54, v11, v54, s94
	s_waitcnt vmcnt(8)
	v_and_b32_e32 v11, 0xffff0000, v13
	v_lshlrev_b32_e32 v10, 16, v13
	v_pk_mul_f32 v[10:11], v[10:11], s[40:41] op_sel_hi:[1,0]
	v_cvt_pk_bf16_f32 v82, v40, v41
	v_cvt_pk_bf16_f32 v84, v8, v9
	v_and_b32_e32 v9, 0xffff0000, v12
	v_lshlrev_b32_e32 v8, 16, v12
	v_and_b32_e32 v13, 0xffff0000, v14
	v_lshlrev_b32_e32 v12, 16, v14
	v_and_b32_e32 v41, 0xffff0000, v15
	v_lshlrev_b32_e32 v40, 16, v15
	v_bfe_u32 v67, v10, 16, 1
	v_pk_mul_f32 v[8:9], v[8:9], s[40:41] op_sel_hi:[1,0]
	v_pk_mul_f32 v[12:13], v[12:13], s[40:41] op_sel_hi:[1,0]
	v_pk_mul_f32 v[14:15], v[40:41], s[40:41] op_sel_hi:[1,0]
	v_add3_u32 v87, v10, v67, s94
	s_movk_i32 s40, 0x110
	v_lshlrev_b32_e32 v10, 4, v56
	v_mul_lo_u32 v214, v138, s40
	v_and_b32_e32 v215, 0xf0, v10
	s_movk_i32 s41, 0x120
	v_add3_u32 v10, s17, v214, v215
	v_mul_lo_u32 v216, v138, s41
	v_mul_lo_u32 v217, v136, s40
	v_mul_lo_u32 v218, v136, s41
	v_mul_lo_u32 v219, v134, s40
	v_mul_lo_u32 v220, v134, s41
	v_mul_lo_u32 v221, v132, s40
	v_mul_lo_u32 v222, v132, s41
	s_mov_b64 s[40:41], 0x10000
	v_bfe_u32 v40, v15, 16, 1
	v_bfe_u32 v41, v14, 16, 1
	v_bfe_u32 v64, v53, 16, 1
	v_bfe_u32 v65, v52, 16, 1
	v_add3_u32 v14, v14, v41, s94
	v_add3_u32 v15, v15, v40, s94
	v_add3_u32 v52, v52, v65, s94
	v_add3_u32 v53, v53, v64, s94
	v_bfe_u32 v64, v13, 16, 1
	v_bfe_u32 v65, v12, 16, 1
	v_bfe_u32 v66, v11, 16, 1
	v_cvt_pk_bf16_f32 v86, v8, v9
	s_waitcnt vmcnt(7)
	ds_write_b128 v10, v[0:3]
	v_add3_u32 v0, s17, v216, v215
	s_waitcnt vmcnt(6)
	ds_write_b128 v0, v[4:7] offset:17408
	v_add3_u32 v0, s17, v217, v215
	v_add3_u32 v88, v11, v66, s94
	v_add3_u32 v12, v12, v65, s94
	v_add3_u32 v13, v13, v64, s94
	v_lshrrev_b32_e32 v9, 2, v56
	s_waitcnt vmcnt(5)
	ds_write_b128 v0, v[16:19]
	v_add3_u32 v0, s17, v218, v215
	s_waitcnt vmcnt(4)
	ds_write_b128 v0, v[20:23] offset:17408
	v_add3_u32 v0, s17, v219, v215
	v_bfe_u32 v8, v56, 2, 2
	v_and_b32_e32 v209, 12, v9
	v_or_b32_e32 v8, v209, v8
	s_waitcnt vmcnt(3)
	ds_write_b128 v0, v[24:27]
	v_add3_u32 v0, s17, v220, v215
	s_waitcnt vmcnt(2)
	ds_write_b128 v0, v[28:31] offset:17408
	v_add3_u32 v0, s17, v221, v215
	s_waitcnt vmcnt(1)
	ds_write_b128 v0, v[32:35]
	v_add3_u32 v0, s17, v222, v215
	s_waitcnt vmcnt(0)
	ds_write_b128 v0, v[36:39] offset:17408
	v_lshl_add_u64 v[0:1], v[42:43], 0, v[44:45]
	v_lshl_add_u64 v[0:1], v[0:1], 1, v[166:167]
	v_lshl_add_u64 v[2:3], s[36:37], 0, v[0:1]
	v_lshl_add_u64 v[0:1], s[38:39], 0, v[0:1]
	global_load_dwordx4 v[16:19], v[2:3], off
	global_load_dwordx4 v[20:23], v[0:1], off
	v_lshl_add_u64 v[0:1], v[46:47], 0, s[40:41]
	v_lshl_add_u64 v[2:3], s[36:37], 0, v[0:1]
	v_lshl_add_u64 v[0:1], s[38:39], 0, v[0:1]
	global_load_dwordx4 v[24:27], v[2:3], off
	global_load_dwordx4 v[28:31], v[0:1], off
	v_lshl_add_u64 v[0:1], v[48:49], 0, s[40:41]
	v_lshl_add_u64 v[2:3], s[36:37], 0, v[0:1]
	v_lshl_add_u64 v[0:1], s[38:39], 0, v[0:1]
	global_load_dwordx4 v[36:39], v[2:3], off
	global_load_dwordx4 v[40:43], v[0:1], off
	v_lshl_add_u64 v[0:1], v[50:51], 0, s[40:41]
	v_lshl_add_u64 v[2:3], s[36:37], 0, v[0:1]
	v_lshl_add_u64 v[0:1], s[38:39], 0, v[0:1]
	global_load_dwordx4 v[64:67], v[2:3], off
	global_load_dwordx4 v[68:71], v[0:1], off
	v_mul_u32_u24_e32 v32, 0x110, v204
	v_add3_u32 v224, s17, v160, v32
	v_lshlrev_b64 v[32:33], 10, v[132:133]
	v_lshlrev_b32_e32 v160, 1, v44
	v_lshl_add_u64 v[32:33], v[32:33], 0, v[160:161]
	v_lshl_add_u64 v[144:145], s[30:31], 0, v[32:33]
	v_add_u32_e32 v32, s23, v132
	v_add_u32_e32 v133, 0xe80, v32
	v_lshlrev_b64 v[32:33], 10, v[134:135]
	v_lshl_add_u64 v[32:33], v[32:33], 0, v[160:161]
	v_lshl_add_u64 v[146:147], s[30:31], 0, v[32:33]
	v_add_u32_e32 v32, s23, v134
	v_add_u32_e32 v135, 0xe80, v32
	v_lshlrev_b64 v[32:33], 10, v[136:137]
	v_lshl_add_u64 v[32:33], v[32:33], 0, v[160:161]
	v_lshl_add_u64 v[148:149], s[30:31], 0, v[32:33]
	v_add_u32_e32 v32, s23, v136
	v_add_u32_e32 v137, 0xe80, v32
	v_lshlrev_b64 v[32:33], 10, v[138:139]
	v_lshl_add_u64 v[32:33], v[32:33], 0, v[160:161]
	v_lshl_add_u64 v[152:153], s[30:31], 0, v[32:33]
	v_add_u32_e32 v32, s23, v138
	v_mul_u32_u24_e32 v8, 0x120, v8
	v_and_b32_e32 v9, 24, v207
	v_readlane_b32 s36, v251, 56
	v_add_u32_e32 v139, 0xe80, v32
	v_mov_b32_e32 v32, 0
	v_add3_u32 v223, v9, s36, v8
	v_mov_b32_e32 v3, v72
	v_mov_b32_e32 v2, v62
	v_mov_b32_e32 v1, v60
	v_perm_b32 v0, v58, v57, s95
	v_mov_b32_e32 v7, v80
	v_mov_b32_e32 v6, v78
	v_mov_b32_e32 v5, v76
	v_mov_b32_e32 v4, v74
	v_perm_b32 v11, v54, v55, s95
	v_perm_b32 v10, v53, v52, s95
	v_mov_b32_e32 v9, v84
	v_mov_b32_e32 v8, v82
	v_perm_b32 v15, v15, v14, s95
	v_perm_b32 v14, v13, v12, s95
	v_perm_b32 v13, v88, v87, s95
	v_mov_b32_e32 v12, v86
	s_mov_b64 s[38:39], 0
	v_mov_b32_e32 v33, v32
	v_mov_b32_e32 v34, v32
	v_mov_b32_e32 v35, v32
	v_mov_b32_e32 v44, v32
	v_mov_b32_e32 v45, v32
	v_mov_b32_e32 v46, v32
	v_mov_b32_e32 v47, v32
	v_mov_b32_e32 v60, v32
	v_mov_b32_e32 v61, v32
	v_mov_b32_e32 v62, v32
	v_mov_b32_e32 v63, v32
	v_mov_b32_e32 v76, v32
	v_mov_b32_e32 v77, v32
	v_mov_b32_e32 v78, v32
	v_mov_b32_e32 v79, v32
	v_mov_b32_e32 v80, v32
	v_mov_b32_e32 v81, v32
	v_mov_b32_e32 v82, v32
	v_mov_b32_e32 v83, v32
	v_mov_b32_e32 v84, v32
	v_mov_b32_e32 v85, v32
	v_mov_b32_e32 v86, v32
	v_mov_b32_e32 v87, v32
	v_mov_b32_e32 v88, v32
	v_mov_b32_e32 v89, v32
	v_mov_b32_e32 v90, v32
	v_mov_b32_e32 v91, v32
	v_mov_b32_e32 v96, v32
	v_mov_b32_e32 v97, v32
	v_mov_b32_e32 v98, v32
	v_mov_b32_e32 v99, v32
	v_mov_b32_e32 v92, v32
	v_mov_b32_e32 v93, v32
	v_mov_b32_e32 v94, v32
	v_mov_b32_e32 v95, v32
	v_mov_b32_e32 v100, v32
	v_mov_b32_e32 v101, v32
	v_mov_b32_e32 v102, v32
	v_mov_b32_e32 v103, v32
	v_mov_b32_e32 v104, v32
	v_mov_b32_e32 v105, v32
	v_mov_b32_e32 v106, v32
	v_mov_b32_e32 v107, v32
	v_mov_b32_e32 v108, v32
	v_mov_b32_e32 v109, v32
	v_mov_b32_e32 v110, v32
	v_mov_b32_e32 v111, v32
	v_mov_b32_e32 v72, v32
	v_mov_b32_e32 v73, v32
	v_mov_b32_e32 v74, v32
	v_mov_b32_e32 v75, v32
	v_mov_b32_e32 v56, v32
	v_mov_b32_e32 v57, v32
	v_mov_b32_e32 v58, v32
	v_mov_b32_e32 v59, v32
	v_mov_b32_e32 v52, v32
	v_mov_b32_e32 v53, v32
	v_mov_b32_e32 v54, v32
	v_mov_b32_e32 v55, v32
	v_mov_b32_e32 v48, v32
	v_mov_b32_e32 v49, v32
	v_mov_b32_e32 v50, v32
	v_mov_b32_e32 v51, v32
	v_mov_b32_e32 v142, v32
	v_mov_b32_e32 v143, v32
	s_waitcnt lgkmcnt(0)
	s_barrier
	s_branch .LBB0_755

.LBB0_754:
	s_mul_i32 s23, s23, 0x8c00
	v_add_u32_e32 v225, s23, v223
	v_add_u32_e32 v113, s23, v224
	ds_read_b128 v[114:117], v113
	ds_read_b128 v[118:121], v113 offset:64
	s_waitcnt lgkmcnt(1)
	v_mfma_f32_16x16x32_bf16 v[114:117], v[114:117], v[0:3], 0
	s_waitcnt lgkmcnt(0)
	v_mfma_f32_16x16x32_bf16 v[156:159], v[118:121], v[4:7], v[114:117]
	ds_read_b128 v[118:121], v113 offset:4416
	s_nop 4
	ds_read_b128 v[114:117], v113 offset:4352
	s_waitcnt lgkmcnt(0)
	v_mfma_f32_16x16x32_bf16 v[114:117], v[114:117], v[0:3], 0
	v_mfma_f32_16x16x32_bf16 v[172:175], v[118:121], v[4:7], v[114:117]
	s_nop 6
	ds_read_b128 v[114:117], v113 offset:8704
	ds_read_b128 v[118:121], v113 offset:8768
	s_waitcnt lgkmcnt(1)
	v_mfma_f32_16x16x32_bf16 v[114:117], v[114:117], v[0:3], 0
	s_waitcnt lgkmcnt(0)
	v_mfma_f32_16x16x32_bf16 v[178:181], v[118:121], v[4:7], v[114:117]
	ds_read_b128 v[118:121], v113 offset:13120
	s_nop 4
	ds_read_b128 v[114:117], v113 offset:13056
	s_waitcnt lgkmcnt(0)
	v_mfma_f32_16x16x32_bf16 v[114:117], v[114:117], v[0:3], 0
	v_mfma_f32_16x16x32_bf16 v[228:231], v[118:121], v[4:7], v[114:117]
	s_nop 6
	ds_read_b128 v[114:117], v113 offset:128
	ds_read_b128 v[118:121], v113 offset:192
	ds_read_b128 v[122:125], v113 offset:4480
	s_waitcnt lgkmcnt(2)
	v_mfma_f32_16x16x32_bf16 v[114:117], v[114:117], v[8:11], 0
	s_waitcnt lgkmcnt(1)
	v_mfma_f32_16x16x32_bf16 v[128:131], v[118:121], v[12:15], v[114:117]
	s_nop 5
	ds_read_b128 v[114:117], v113 offset:4544
	s_waitcnt lgkmcnt(1)
	v_mfma_f32_16x16x32_bf16 v[122:125], v[122:125], v[8:11], 0
	s_waitcnt lgkmcnt(0)
	v_mfma_f32_16x16x32_bf16 v[120:123], v[114:117], v[12:15], v[122:125]
	ds_read_b128 v[114:117], v113 offset:8832
	s_nop 4
	ds_read_b128 v[124:127], v113 offset:8896
	s_waitcnt lgkmcnt(1)
	v_mfma_f32_16x16x32_bf16 v[114:117], v[114:117], v[8:11], 0
	s_waitcnt lgkmcnt(0)
	v_mfma_f32_16x16x32_bf16 v[116:119], v[124:127], v[12:15], v[114:117]
	ds_read_b128 v[124:127], v113 offset:13248
	ds_read_b128 v[182:185], v113 offset:13184
	s_waitcnt lgkmcnt(0)
	v_mfma_f32_16x16x32_bf16 v[182:185], v[182:185], v[8:11], 0
	v_mfma_f32_16x16x32_bf16 v[124:127], v[124:127], v[12:15], v[182:185]
	v_max3_f32 v113, v156, s8, v157
	v_max3_f32 v113, v113, v158, v159
	v_max3_f32 v113, v113, v172, v173
	v_max3_f32 v113, v113, v174, v175
	v_max3_f32 v113, v113, v178, v179
	v_max3_f32 v113, v113, v180, v181
	v_max3_f32 v113, v113, v228, v229
	v_max3_f32 v113, v113, v230, v231
	ds_bpermute_b32 v114, v205, v113
	s_waitcnt lgkmcnt(0)
	v_max_f32_e32 v114, v114, v114
	v_max_f32_e32 v113, v113, v114
	ds_bpermute_b32 v114, v141, v113
	s_waitcnt lgkmcnt(0)
	v_max3_f32 v226, v112, v113, v114
	v_sub_f32_e32 v114, v157, v226
	v_mul_f32_e32 v114, 0x3fb8aa3b, v114
	v_exp_f32_e32 v176, v114
	v_sub_f32_e32 v114, v158, v226
	v_sub_f32_e32 v113, v156, v226
	v_mul_f32_e32 v114, 0x3fb8aa3b, v114
	v_mul_f32_e32 v113, 0x3fb8aa3b, v113
	v_exp_f32_e32 v158, v114
	v_sub_f32_e32 v114, v159, v226
	v_exp_f32_e32 v156, v113
	v_mul_f32_e32 v114, 0x3fb8aa3b, v114
	v_exp_f32_e32 v182, v114
	v_sub_f32_e32 v114, v172, v226
	v_mul_f32_e32 v114, 0x3fb8aa3b, v114
	v_exp_f32_e32 v172, v114
	v_sub_f32_e32 v114, v173, v226
	v_add_f32_e32 v113, 0, v156
	v_mul_f32_e32 v114, 0x3fb8aa3b, v114
	v_add_f32_e32 v113, v176, v113
	v_exp_f32_e32 v184, v114
	v_add_f32_e32 v113, v158, v113
	v_add_f32_e32 v113, v182, v113
	v_add_f32_e32 v113, v172, v113
	v_add_f32_e32 v187, v184, v113
	v_sub_f32_e32 v113, v174, v226
	v_mul_f32_e32 v113, 0x3fb8aa3b, v113
	v_exp_f32_e32 v177, v113
	v_sub_f32_e32 v113, v175, v226
	v_mul_f32_e32 v113, 0x3fb8aa3b, v113
	v_exp_f32_e32 v183, v113
	v_sub_f32_e32 v113, v178, v226
	v_mul_f32_e32 v113, 0x3fb8aa3b, v113
	v_exp_f32_e32 v155, v113
	v_sub_f32_e32 v113, v179, v226
	v_mul_f32_e32 v113, 0x3fb8aa3b, v113
	v_exp_f32_e32 v159, v113
	v_sub_f32_e32 v113, v180, v226
	v_mul_f32_e32 v113, 0x3fb8aa3b, v113
	v_exp_f32_e32 v157, v113
	v_sub_f32_e32 v113, v181, v226
	v_mul_f32_e32 v113, 0x3fb8aa3b, v113
	v_exp_f32_e32 v175, v113
	v_sub_f32_e32 v113, v228, v226
	v_mul_f32_e32 v113, 0x3fb8aa3b, v113
	v_exp_f32_e32 v173, v113
	v_sub_f32_e32 v113, v229, v226
	v_mul_f32_e32 v113, 0x3fb8aa3b, v113
	v_exp_f32_e32 v181, v113
	v_sub_f32_e32 v113, v230, v226
	v_sub_f32_e32 v112, v112, v226
	v_mul_f32_e32 v113, 0x3fb8aa3b, v113
	v_mul_f32_e32 v112, 0x3fb8aa3b, v112
	v_exp_f32_e32 v179, v113
	v_sub_f32_e32 v113, v231, v226
	v_mul_f32_e32 v113, 0x3fb8aa3b, v113
	v_exp_f32_e32 v160, v112
	v_exp_f32_e32 v185, v113
	v_pk_mul_f32 v[112:113], v[108:109], v[160:161] op_sel_hi:[1,0]
	v_pk_mul_f32 v[108:109], v[104:105], v[160:161] op_sel_hi:[1,0]
	v_pk_mul_f32 v[104:105], v[100:101], v[160:161] op_sel_hi:[1,0]
	v_pk_mul_f32 v[100:101], v[92:93], v[160:161] op_sel_hi:[1,0]
	v_pk_mul_f32 v[92:93], v[96:97], v[160:161] op_sel_hi:[1,0]
	v_max3_f32 v96, v128, s8, v129
	v_max3_f32 v96, v96, v130, v131
	v_max3_f32 v96, v96, v120, v121
	v_max3_f32 v96, v96, v122, v123
	v_max3_f32 v96, v96, v116, v117
	v_max3_f32 v96, v96, v118, v119
	v_max3_f32 v96, v96, v124, v125
	v_cvt_pk_bf16_f32 v242, v177, v183
	v_max3_f32 v96, v96, v126, v127
	v_cvt_pk_bf16_f32 v234, v179, v185
	ds_bpermute_b32 v97, v205, v96
	v_pk_mul_f32 v[114:115], v[110:111], v[160:161] op_sel_hi:[1,0]
	v_pk_mul_f32 v[110:111], v[106:107], v[160:161] op_sel_hi:[1,0]
	v_pk_mul_f32 v[106:107], v[102:103], v[160:161] op_sel_hi:[1,0]
	v_pk_mul_f32 v[102:103], v[94:95], v[160:161] op_sel_hi:[1,0]
	s_waitcnt lgkmcnt(0)
	v_max_f32_e32 v97, v97, v97
	v_max_f32_e32 v96, v96, v97
	ds_bpermute_b32 v97, v141, v96
	v_pk_mul_f32 v[94:95], v[98:99], v[160:161] op_sel_hi:[1,0]
	s_waitcnt lgkmcnt(0)
	v_max3_f32 v227, v154, v96, v97
	v_sub_f32_e32 v98, v129, v227
	v_mul_f32_e32 v98, 0x3fb8aa3b, v98
	v_exp_f32_e32 v129, v98
	v_sub_f32_e32 v98, v130, v227
	v_sub_f32_e32 v97, v128, v227
	v_mul_f32_e32 v98, 0x3fb8aa3b, v98
	v_mul_f32_e32 v97, 0x3fb8aa3b, v97
	v_exp_f32_e32 v130, v98
	v_sub_f32_e32 v98, v131, v227
	v_exp_f32_e32 v128, v97
	v_mul_f32_e32 v98, 0x3fb8aa3b, v98
	v_exp_f32_e32 v131, v98
	v_sub_f32_e32 v98, v120, v227
	v_mul_f32_e32 v98, 0x3fb8aa3b, v98
	v_exp_f32_e32 v244, v98
	v_sub_f32_e32 v98, v121, v227
	v_add_f32_e32 v97, 0, v128
	v_mul_f32_e32 v98, 0x3fb8aa3b, v98
	v_add_f32_e32 v97, v129, v97
	v_exp_f32_e32 v245, v98
	v_add_f32_e32 v97, v130, v97
	v_add_f32_e32 v97, v131, v97
	v_add_f32_e32 v97, v244, v97
	v_add_f32_e32 v186, v245, v97
	v_sub_f32_e32 v97, v122, v227
	v_mul_f32_e32 v97, 0x3fb8aa3b, v97
	v_cvt_pk_bf16_f32 v237, v156, v176
	v_exp_f32_e32 v176, v97
	v_sub_f32_e32 v97, v123, v227
	v_bfe_u32 v174, v182, 16, 1
	v_mul_f32_e32 v97, 0x3fb8aa3b, v97
	v_add3_u32 v239, v182, v174, s94
	v_exp_f32_e32 v182, v97
	v_sub_f32_e32 v97, v116, v227
	v_mul_f32_e32 v97, 0x3fb8aa3b, v97
	v_bfe_u32 v178, v158, 16, 1
	v_sub_f32_e32 v96, v154, v227
	v_exp_f32_e32 v154, v97
	v_sub_f32_e32 v97, v117, v227
	v_add3_u32 v238, v158, v178, s94
	v_mul_f32_e32 v97, 0x3fb8aa3b, v97
	v_exp_f32_e32 v158, v97
	v_sub_f32_e32 v97, v118, v227
	v_mul_f32_e32 v97, 0x3fb8aa3b, v97
	v_cvt_pk_bf16_f32 v231, v157, v175
	v_exp_f32_e32 v156, v97
	v_sub_f32_e32 v97, v119, v227
	v_mul_f32_e32 v97, 0x3fb8aa3b, v97
	v_exp_f32_e32 v174, v97
	v_sub_f32_e32 v97, v124, v227
	v_cvt_pk_bf16_f32 v240, v172, v184
	v_mul_f32_e32 v97, 0x3fb8aa3b, v97
	v_cvt_pk_bf16_f32 v229, v155, v159
	v_exp_f32_e32 v172, v97
	v_sub_f32_e32 v97, v125, v227
	v_mul_f32_e32 v97, 0x3fb8aa3b, v97
	v_exp_f32_e32 v180, v97
	v_sub_f32_e32 v97, v126, v227
	v_mul_f32_e32 v97, 0x3fb8aa3b, v97
	v_exp_f32_e32 v178, v97
	v_sub_f32_e32 v97, v127, v227
	v_mul_f32_e32 v96, 0x3fb8aa3b, v96
	v_mul_f32_e32 v97, 0x3fb8aa3b, v97
	v_exp_f32_e32 v184, v97
	v_exp_f32_e32 v120, v96
	v_pk_add_f32 v[96:97], v[176:177], v[186:187]
	v_pk_add_f32 v[96:97], v[182:183], v[96:97]
	v_mov_b32_e32 v121, v160
	v_pk_add_f32 v[96:97], v[154:155], v[96:97]
	v_cvt_pk_bf16_f32 v232, v173, v181
	v_pk_add_f32 v[96:97], v[158:159], v[96:97]
	v_pk_mul_f32 v[98:99], v[62:63], v[120:121] op_sel_hi:[1,0]
	v_pk_add_f32 v[96:97], v[156:157], v[96:97]
	v_pk_mul_f32 v[62:63], v[34:35], v[120:121] op_sel_hi:[1,0]
	v_pk_add_f32 v[96:97], v[174:175], v[96:97]
	v_pk_mul_f32 v[34:35], v[74:75], v[120:121] op_sel_hi:[1,0]
	v_pk_add_f32 v[96:97], v[172:173], v[96:97]
	v_pk_add_f32 v[96:97], v[180:181], v[96:97]
	v_pk_add_f32 v[96:97], v[178:179], v[96:97]
	v_pk_mul_f32 v[90:91], v[90:91], v[160:161] op_sel_hi:[1,0]
	v_pk_add_f32 v[96:97], v[184:185], v[96:97]
	v_pk_mul_f32 v[88:89], v[88:89], v[160:161] op_sel_hi:[1,0]
	v_pk_mul_f32 v[86:87], v[86:87], v[160:161] op_sel_hi:[1,0]
	v_pk_mul_f32 v[84:85], v[84:85], v[160:161] op_sel_hi:[1,0]
	v_pk_mul_f32 v[82:83], v[82:83], v[160:161] op_sel_hi:[1,0]
	v_pk_mul_f32 v[80:81], v[80:81], v[160:161] op_sel_hi:[1,0]
	v_pk_fma_f32 v[142:143], v[142:143], v[120:121], v[96:97]
	v_pk_mul_f32 v[118:119], v[78:79], v[120:121] op_sel_hi:[1,0]
	v_pk_mul_f32 v[116:117], v[76:77], v[120:121] op_sel_hi:[1,0]
	v_pk_mul_f32 v[96:97], v[60:61], v[120:121] op_sel_hi:[1,0]
	v_pk_mul_f32 v[78:79], v[46:47], v[120:121] op_sel_hi:[1,0]
	v_pk_mul_f32 v[76:77], v[44:45], v[120:121] op_sel_hi:[1,0]
	v_pk_mul_f32 v[60:61], v[32:33], v[120:121] op_sel_hi:[1,0]
	v_pk_mul_f32 v[32:33], v[72:73], v[120:121] op_sel_hi:[1,0]
	v_pk_mul_f32 v[46:47], v[58:59], v[120:121] op_sel_hi:[1,0]
	v_pk_mul_f32 v[44:45], v[56:57], v[120:121] op_sel_hi:[1,0]
	v_bfe_u32 v74, v156, 16, 1
	v_bfe_u32 v75, v154, 16, 1
	v_cvt_pk_bf16_f32 v173, v128, v129
	v_cvt_pk_bf16_f32 v175, v130, v131
	v_cvt_pk_bf16_f32 v177, v244, v245
	v_bfe_u32 v58, v174, 16, 1
	v_bfe_u32 v59, v158, 16, 1
	v_add3_u32 v247, v154, v75, s94
	v_add3_u32 v248, v156, v74, s94
	v_add_u32_e32 v128, 0x1200, v225
	v_add_u32_e32 v129, 32, v225
	v_add_u32_e32 v130, 0x1220, v225
	v_add_u32_e32 v131, 64, v225
	v_add_u32_e32 v154, 0x1240, v225
	v_add_u32_e32 v156, 0x60, v225
	v_pk_mul_f32 v[54:55], v[54:55], v[120:121] op_sel_hi:[1,0]
	v_pk_mul_f32 v[52:53], v[52:53], v[120:121] op_sel_hi:[1,0]
	v_pk_mul_f32 v[50:51], v[50:51], v[120:121] op_sel_hi:[1,0]
	v_pk_mul_f32 v[48:49], v[48:49], v[120:121] op_sel_hi:[1,0]
	v_add3_u32 v158, v158, v59, s94
	v_add3_u32 v244, v174, v58, s94
	v_cvt_pk_bf16_f32 v249, v172, v180
	v_cvt_pk_bf16_f32 v250, v178, v184
	v_add_u32_e32 v172, 0x1260, v225
	ds_read_b64_tr_b16 v[124:125], v225
	ds_read_b64_tr_b16 v[126:127], v128
	ds_read_b64_tr_b16 v[120:121], v129
	ds_read_b64_tr_b16 v[122:123], v130
	ds_read_b64_tr_b16 v[72:73], v131
	ds_read_b64_tr_b16 v[74:75], v154
	ds_read_b64_tr_b16 v[56:57], v156
	ds_read_b64_tr_b16 v[58:59], v172
	s_waitcnt lgkmcnt(0)
	v_mov_b32_e32 v131, v242
	v_mov_b32_e32 v130, v240
	v_perm_b32 v129, v239, v238, s95
	v_mov_b32_e32 v128, v237
	v_mov_b32_e32 v156, v177
	v_mov_b32_e32 v155, v175
	v_mov_b32_e32 v154, v173
	v_cvt_pk_bf16_f32 v157, v176, v182
	v_mfma_f32_16x16x32_bf16 v[112:115], v[124:127], v[128:131], v[112:115]
	s_nop 0
	v_mfma_f32_16x16x32_bf16 v[116:119], v[124:127], v[154:157], v[116:119]
	v_mfma_f32_16x16x32_bf16 v[124:127], v[120:123], v[128:131], v[108:111]
	v_mfma_f32_16x16x32_bf16 v[96:99], v[120:123], v[154:157], v[96:99]
	v_mfma_f32_16x16x32_bf16 v[120:123], v[72:75], v[128:131], v[104:107]
	v_mfma_f32_16x16x32_bf16 v[72:75], v[72:75], v[154:157], v[76:79]
	v_mfma_f32_16x16x32_bf16 v[172:175], v[56:59], v[128:131], v[100:103]
	v_mfma_f32_16x16x32_bf16 v[56:59], v[56:59], v[154:157], v[60:63]
	v_add_u32_e32 v108, 0x80, v225
	v_add_u32_e32 v109, 0x1280, v225
	v_add_u32_e32 v110, 0xa0, v225
	v_add_u32_e32 v111, 0x12a0, v225
	v_add_u32_e32 v159, 0xc0, v225
	v_add_u32_e32 v160, 0x12c0, v225
	v_add_u32_e32 v176, 0xe0, v225
	v_add_u32_e32 v177, 0x12e0, v225
	ds_read_b64_tr_b16 v[104:105], v108
	ds_read_b64_tr_b16 v[106:107], v109
	ds_read_b64_tr_b16 v[100:101], v110
	ds_read_b64_tr_b16 v[102:103], v111
	ds_read_b64_tr_b16 v[76:77], v159
	ds_read_b64_tr_b16 v[78:79], v160
	ds_read_b64_tr_b16 v[60:61], v176
	ds_read_b64_tr_b16 v[62:63], v177
	s_waitcnt lgkmcnt(0)
	s_nop 0
	v_mfma_f32_16x16x32_bf16 v[88:91], v[100:103], v[128:131], v[88:91]
	v_mfma_f32_16x16x32_bf16 v[84:87], v[76:79], v[128:131], v[84:87]
	v_mfma_f32_16x16x32_bf16 v[52:55], v[76:79], v[154:157], v[52:55]
	v_mfma_f32_16x16x32_bf16 v[80:83], v[60:63], v[128:131], v[80:83]
	v_mfma_f32_16x16x32_bf16 v[48:51], v[60:63], v[154:157], v[48:51]
	v_mfma_f32_16x16x32_bf16 v[176:179], v[104:107], v[128:131], v[92:95]
	v_mfma_f32_16x16x32_bf16 v[180:183], v[104:107], v[154:157], v[32:35]
	v_mfma_f32_16x16x32_bf16 v[184:187], v[100:103], v[154:157], v[44:47]
	s_nop 0
	v_add_u32_e32 v92, 0x2400, v225
	v_add_u32_e32 v93, 0x3600, v225
	v_add_u32_e32 v94, 0x2420, v225
	v_add_u32_e32 v95, 0x3620, v225
	v_add_u32_e32 v100, 0x2440, v225
	v_add_u32_e32 v101, 0x3640, v225
	v_add_u32_e32 v102, 0x2460, v225
	v_add_u32_e32 v103, 0x3660, v225
	ds_read_b64_tr_b16 v[76:77], v92
	ds_read_b64_tr_b16 v[78:79], v93
	ds_read_b64_tr_b16 v[60:61], v94
	ds_read_b64_tr_b16 v[62:63], v95
	ds_read_b64_tr_b16 v[44:45], v100
	ds_read_b64_tr_b16 v[46:47], v101
	ds_read_b64_tr_b16 v[32:33], v102
	ds_read_b64_tr_b16 v[34:35], v103
	s_waitcnt lgkmcnt(0)
	v_mov_b32_e32 v131, v234
	v_mov_b32_e32 v130, v232
	v_mov_b32_e32 v129, v231
	v_mov_b32_e32 v128, v229
	v_mov_b32_e32 v157, v250
	v_mov_b32_e32 v156, v249
	v_perm_b32 v155, v244, v248, s95
	v_perm_b32 v154, v158, v247, s95
	v_mfma_f32_16x16x32_bf16 v[108:111], v[76:79], v[128:131], v[112:115]
	s_nop 0
	v_mfma_f32_16x16x32_bf16 v[76:79], v[76:79], v[154:157], v[116:119]
	v_mfma_f32_16x16x32_bf16 v[104:107], v[60:63], v[128:131], v[124:127]
	v_mfma_f32_16x16x32_bf16 v[60:63], v[60:63], v[154:157], v[96:99]
	v_mfma_f32_16x16x32_bf16 v[100:103], v[44:47], v[128:131], v[120:123]
	v_mfma_f32_16x16x32_bf16 v[44:47], v[44:47], v[154:157], v[72:75]
	v_mfma_f32_16x16x32_bf16 v[92:95], v[32:35], v[128:131], v[172:175]
	v_mfma_f32_16x16x32_bf16 v[32:35], v[32:35], v[154:157], v[56:59]
	v_add_u32_e32 v96, 0x2480, v225
	v_add_u32_e32 v97, 0x3680, v225
	v_add_u32_e32 v98, 0x24a0, v225
	v_add_u32_e32 v99, 0x36a0, v225
	v_add_u32_e32 v120, 0x24c0, v225
	v_add_u32_e32 v121, 0x36c0, v225
	v_add_u32_e32 v122, 0x24e0, v225
	v_add_u32_e32 v123, 0x36e0, v225
	ds_read_b64_tr_b16 v[72:73], v96
	ds_read_b64_tr_b16 v[74:75], v97
	ds_read_b64_tr_b16 v[56:57], v98
	ds_read_b64_tr_b16 v[58:59], v99
	ds_read_b64_tr_b16 v[116:117], v120
	ds_read_b64_tr_b16 v[118:119], v121
	ds_read_b64_tr_b16 v[112:113], v122
	ds_read_b64_tr_b16 v[114:115], v123
	s_waitcnt lgkmcnt(0)
	s_nop 0
	v_mfma_f32_16x16x32_bf16 v[96:99], v[72:75], v[128:131], v[176:179]
	v_mfma_f32_16x16x32_bf16 v[72:75], v[72:75], v[154:157], v[180:183]
	v_mfma_f32_16x16x32_bf16 v[88:91], v[56:59], v[128:131], v[88:91]
	v_mfma_f32_16x16x32_bf16 v[56:59], v[56:59], v[154:157], v[184:187]
	v_mfma_f32_16x16x32_bf16 v[84:87], v[116:119], v[128:131], v[84:87]
	v_mfma_f32_16x16x32_bf16 v[52:55], v[116:119], v[154:157], v[52:55]
	v_mfma_f32_16x16x32_bf16 v[80:83], v[112:115], v[128:131], v[80:83]
	v_mfma_f32_16x16x32_bf16 v[48:51], v[112:115], v[154:157], v[48:51]
	s_add_u32 s38, s38, 0x10000
	s_addc_u32 s39, s39, 0
	s_add_i32 s22, s22, 1
	v_add_u32_e32 v133, 64, v133
	v_add_u32_e32 v135, 64, v135
	v_add_u32_e32 v137, 64, v137
	v_add_u32_e32 v139, 64, v139
	s_cmp_lg_u32 s38, 0x180000
	v_mov_b32_e32 v154, v227
	v_mov_b32_e32 v112, v226
	s_barrier
	s_cbranch_scc0 .LBB0_773

.LBB0_1050:
	global_load_dwordx2 v[52:53], v[40:41], off offset:-2048
	global_load_dwordx2 v[54:55], v[40:41], off offset:-1536
	global_load_dwordx2 v[56:57], v[40:41], off offset:-1024
	global_load_dwordx2 v[58:59], v[40:41], off offset:-512
	global_load_dwordx2 v[60:61], v[40:41], off
	global_load_dwordx2 v[62:63], v[40:41], off offset:512
	global_load_dwordx2 v[64:65], v[40:41], off offset:1024
	global_load_dwordx2 v[66:67], v[40:41], off offset:1536
	global_load_dwordx4 v[0:3], v[8:9], off
	global_load_dwordx4 v[4:7], v[10:11], off
	v_add_u32_e32 v44, s8, v44
	v_lshl_add_u64 v[40:41], v[40:41], 0, s[10:11]
	s_waitcnt vmcnt(9)
	v_and_b32_e32 v69, 0xffff0000, v52
	v_lshlrev_b32_e32 v68, 16, v52
	v_and_b32_e32 v71, 0xffff0000, v53
	v_lshlrev_b32_e32 v70, 16, v53
	s_waitcnt vmcnt(8)
	v_and_b32_e32 v53, 0xffff0000, v54
	v_lshlrev_b32_e32 v52, 16, v54
	v_and_b32_e32 v73, 0xffff0000, v55
	v_lshlrev_b32_e32 v72, 16, v55
	s_waitcnt vmcnt(7)
	v_and_b32_e32 v55, 0xffff0000, v56
	v_lshlrev_b32_e32 v54, 16, v56
	v_and_b32_e32 v75, 0xffff0000, v57
	v_lshlrev_b32_e32 v74, 16, v57
	s_waitcnt vmcnt(6)
	v_and_b32_e32 v57, 0xffff0000, v58
	v_lshlrev_b32_e32 v56, 16, v58
	v_and_b32_e32 v77, 0xffff0000, v59
	v_lshlrev_b32_e32 v76, 16, v59
	s_waitcnt vmcnt(5)
	v_and_b32_e32 v59, 0xffff0000, v60
	v_lshlrev_b32_e32 v58, 16, v60
	v_and_b32_e32 v79, 0xffff0000, v61
	v_lshlrev_b32_e32 v78, 16, v61
	s_waitcnt vmcnt(4)
	v_and_b32_e32 v61, 0xffff0000, v62
	v_lshlrev_b32_e32 v60, 16, v62
	v_and_b32_e32 v81, 0xffff0000, v63
	v_lshlrev_b32_e32 v80, 16, v63
	s_waitcnt vmcnt(3)
	v_and_b32_e32 v63, 0xffff0000, v64
	v_lshlrev_b32_e32 v62, 16, v64
	v_and_b32_e32 v83, 0xffff0000, v65
	v_lshlrev_b32_e32 v82, 16, v65
	s_waitcnt vmcnt(2)
	v_and_b32_e32 v65, 0xffff0000, v66
	v_lshlrev_b32_e32 v64, 16, v66
	v_add_f32_e32 v100, v69, v68
	v_and_b32_e32 v85, 0xffff0000, v67
	v_lshlrev_b32_e32 v84, 16, v67
	v_add_f32_e32 v101, v53, v52
	v_mov_b32_e32 v66, v58
	v_mov_b32_e32 v67, v60
	v_mov_b32_e32 v86, v59
	v_mov_b32_e32 v87, v61
	v_mov_b32_e32 v92, v62
	v_mov_b32_e32 v93, v64
	v_mov_b32_e32 v94, v63
	v_mov_b32_e32 v95, v65
	v_add_f32_e32 v100, v100, v70
	v_add_f32_e32 v102, v55, v54
	v_mov_b32_e32 v88, v78
	v_mov_b32_e32 v89, v80
	v_add_f32_e32 v101, v101, v72
	v_pk_add_f32 v[66:67], v[66:67], v[86:87]
	v_pk_add_f32 v[86:87], v[92:93], v[94:95]
	v_add_f32_e32 v92, v100, v71
	v_add_f32_e32 v103, v57, v56
	v_add_f32_e32 v102, v102, v74
	v_add_f32_e32 v93, v101, v73
	v_pk_add_f32 v[66:67], v[66:67], v[88:89]
	v_add_f32_e32 v88, 0, v92
	v_add_f32_e32 v103, v103, v76
	v_add_f32_e32 v94, v102, v75
	v_add_f32_e32 v88, v88, v93
	v_mov_b32_e32 v90, v79
	v_mov_b32_e32 v91, v81
	v_add_f32_e32 v95, v103, v77
	v_add_f32_e32 v88, v88, v94
	v_mov_b32_e32 v96, v82
	v_mov_b32_e32 v97, v84
	v_pk_add_f32 v[66:67], v[66:67], v[90:91]
	v_add_f32_e32 v88, v88, v95
	v_mov_b32_e32 v98, v83
	v_mov_b32_e32 v99, v85
	v_pk_add_f32 v[86:87], v[86:87], v[96:97]
	v_add_f32_e32 v66, v88, v66
	v_pk_add_f32 v[86:87], v[86:87], v[98:99]
	v_add_f32_e32 v66, v66, v67
	v_add_f32_e32 v66, v66, v86
	v_add_f32_e32 v66, v66, v87
	s_waitcnt lgkmcnt(0)
	v_mov_b32_e32 v67, v66
	s_nop 1
	v_permlane32_swap_b32_e32 v67, v66
	v_add_f32_e32 v66, v66, v67
	s_waitcnt lgkmcnt(0)
	v_mov_b32_e32 v67, v66
	s_nop 1
	v_permlane16_swap_b32_e32 v67, v66
	v_add_f32_e32 v66, v66, v67
	s_waitcnt lgkmcnt(0)
	s_nop 1
	v_add_f32_dpp v66, v66, v66 row_mirror row_mask:0xf bank_mask:0xf
	s_waitcnt lgkmcnt(0)
	s_nop 1
	v_add_f32_dpp v66, v66, v66 row_half_mirror row_mask:0xf bank_mask:0xf
	s_waitcnt lgkmcnt(0)
	s_nop 1
	v_add_f32_dpp v66, v66, v66 quad_perm:[2,3,0,1] row_mask:0xf bank_mask:0xf
	s_waitcnt lgkmcnt(0)
	s_nop 1
	v_add_f32_dpp v66, v66, v66 quad_perm:[1,0,3,2] row_mask:0xf bank_mask:0xf
	v_mul_f32_e32 v66, 0x3a000000, v66
	v_pk_add_f32 v[68:69], v[68:69], v[66:67] op_sel_hi:[1,0] neg_lo:[0,1] neg_hi:[0,1]
	v_pk_add_f32 v[52:53], v[52:53], v[66:67] op_sel_hi:[1,0] neg_lo:[0,1] neg_hi:[0,1]
	v_pk_add_f32 v[62:63], v[62:63], v[66:67] op_sel_hi:[1,0] neg_lo:[0,1] neg_hi:[0,1]
	v_pk_add_f32 v[64:65], v[64:65], v[66:67] op_sel_hi:[1,0] neg_lo:[0,1] neg_hi:[0,1]
	v_pk_add_f32 v[70:71], v[70:71], v[66:67] op_sel_hi:[1,0] neg_lo:[0,1] neg_hi:[0,1]
	v_pk_add_f32 v[72:73], v[72:73], v[66:67] op_sel_hi:[1,0] neg_lo:[0,1] neg_hi:[0,1]
	v_pk_add_f32 v[54:55], v[54:55], v[66:67] op_sel_hi:[1,0] neg_lo:[0,1] neg_hi:[0,1]
	v_pk_add_f32 v[74:75], v[74:75], v[66:67] op_sel_hi:[1,0] neg_lo:[0,1] neg_hi:[0,1]
	v_pk_add_f32 v[56:57], v[56:57], v[66:67] op_sel_hi:[1,0] neg_lo:[0,1] neg_hi:[0,1]
	v_pk_add_f32 v[76:77], v[76:77], v[66:67] op_sel_hi:[1,0] neg_lo:[0,1] neg_hi:[0,1]
	v_pk_add_f32 v[58:59], v[58:59], v[66:67] op_sel_hi:[1,0] neg_lo:[0,1] neg_hi:[0,1]
	v_pk_add_f32 v[78:79], v[78:79], v[66:67] op_sel_hi:[1,0] neg_lo:[0,1] neg_hi:[0,1]
	v_pk_add_f32 v[60:61], v[60:61], v[66:67] op_sel_hi:[1,0] neg_lo:[0,1] neg_hi:[0,1]
	v_pk_add_f32 v[80:81], v[80:81], v[66:67] op_sel_hi:[1,0] neg_lo:[0,1] neg_hi:[0,1]
	v_pk_add_f32 v[82:83], v[82:83], v[66:67] op_sel_hi:[1,0] neg_lo:[0,1] neg_hi:[0,1]
	v_pk_add_f32 v[66:67], v[84:85], v[66:67] op_sel_hi:[1,0] neg_lo:[0,1] neg_hi:[0,1]
	v_pk_mul_f32 v[84:85], v[68:69], v[68:69]
	v_pk_mul_f32 v[88:89], v[52:53], v[52:53]
	v_mov_b32_e32 v110, v65
	v_mov_b32_e32 v111, v63
	v_pk_mul_f32 v[86:87], v[70:71], v[70:71]
	v_pk_mul_f32 v[90:91], v[72:73], v[72:73]
	v_pk_mul_f32 v[92:93], v[54:55], v[54:55]
	v_mov_b32_e32 v108, v64
	v_mov_b32_e32 v109, v62
	v_pk_mul_f32 v[110:111], v[110:111], v[110:111]
	v_add_f32_e32 v116, v88, v89
	v_add_f32_e32 v117, v84, v85
	v_pk_mul_f32 v[94:95], v[74:75], v[74:75]
	v_pk_mul_f32 v[96:97], v[56:57], v[56:57]
	v_mov_b32_e32 v102, v61
	v_mov_b32_e32 v103, v59
	v_mov_b32_e32 v112, v66
	v_mov_b32_e32 v113, v82
	v_add_f32_e32 v92, v92, v93
	v_pk_fma_f32 v[88:89], v[108:109], v[108:109], v[110:111]
	v_add_f32_e32 v90, v90, v116
	v_add_f32_e32 v86, v86, v117
	v_pk_mul_f32 v[98:99], v[76:77], v[76:77]
	v_mov_b32_e32 v100, v60
	v_mov_b32_e32 v101, v58
	v_mov_b32_e32 v114, v67
	v_mov_b32_e32 v115, v83
	v_pk_mul_f32 v[102:103], v[102:103], v[102:103]
	v_add_f32_e32 v93, v96, v97
	v_add_f32_e32 v92, v94, v92
	v_pk_fma_f32 v[88:89], v[112:113], v[112:113], v[88:89]
	v_add_f32_e32 v90, v91, v90
	v_add_f32_e32 v91, v87, v86
	v_mov_b32_e32 v104, v80
	v_mov_b32_e32 v105, v78
	v_pk_fma_f32 v[84:85], v[100:101], v[100:101], v[102:103]
	v_add_f32_e32 v93, v98, v93
	v_add_f32_e32 v92, v95, v92
	v_pk_fma_f32 v[86:87], v[114:115], v[114:115], v[88:89]
	v_add_f32_e32 v88, v91, v90
	v_mov_b32_e32 v106, v81
	v_mov_b32_e32 v107, v79
	v_pk_fma_f32 v[84:85], v[104:105], v[104:105], v[84:85]
	v_add_f32_e32 v93, v99, v93
	v_add_f32_e32 v88, v92, v88
	v_pk_fma_f32 v[84:85], v[106:107], v[106:107], v[84:85]
	v_add_f32_e32 v88, v93, v88
	v_add_f32_e32 v85, v85, v88
	v_add_f32_e32 v84, v84, v85
	v_add_f32_e32 v84, v87, v84
	v_add_f32_e32 v84, v86, v84
	s_waitcnt lgkmcnt(0)
	v_mov_b32_e32 v85, v84
	s_nop 1
	v_permlane32_swap_b32_e32 v85, v84
	v_add_f32_e32 v84, v84, v85
	s_waitcnt lgkmcnt(0)
	v_mov_b32_e32 v85, v84
	s_nop 1
	v_permlane16_swap_b32_e32 v85, v84
	v_add_f32_e32 v84, v84, v85
	s_waitcnt lgkmcnt(0)
	s_nop 1
	v_add_f32_dpp v84, v84, v84 row_mirror row_mask:0xf bank_mask:0xf
	s_waitcnt lgkmcnt(0)
	s_nop 1
	v_add_f32_dpp v84, v84, v84 row_half_mirror row_mask:0xf bank_mask:0xf
	s_waitcnt lgkmcnt(0)
	s_nop 1
	v_add_f32_dpp v84, v84, v84 quad_perm:[2,3,0,1] row_mask:0xf bank_mask:0xf
	s_waitcnt lgkmcnt(0)
	s_nop 1
	v_add_f32_dpp v84, v84, v84 quad_perm:[1,0,3,2] row_mask:0xf bank_mask:0xf
	v_fmamk_f32 v84, v84, 0x3a000000, v51
	v_mul_f32_e32 v85, 0x4b800000, v84
	v_cmp_gt_f32_e32 vcc, s2, v84
	s_nop 1
	v_cndmask_b32_e32 v84, v84, v85, vcc
	v_rsq_f32_e32 v84, v84
	s_nop 0
	v_mul_f32_e32 v85, 0x45800000, v84
	v_cndmask_b32_e32 v84, v84, v85, vcc
	v_pk_mul_f32 v[68:69], v[68:69], v[84:85] op_sel_hi:[1,0]
	v_pk_mul_f32 v[70:71], v[70:71], v[84:85] op_sel_hi:[1,0]
	s_waitcnt vmcnt(0)
	v_pk_fma_f32 v[0:1], v[0:1], v[68:69], v[4:5]
	v_pk_fma_f32 v[2:3], v[2:3], v[70:71], v[6:7]
	global_store_dwordx4 v[42:43], v[0:3], off offset:-4096
	global_load_dwordx4 v[0:3], v[12:13], off
	s_nop 0
	global_load_dwordx4 v[4:7], v[14:15], off
	v_pk_mul_f32 v[52:53], v[52:53], v[84:85] op_sel_hi:[1,0]
	v_pk_mul_f32 v[68:69], v[72:73], v[84:85] op_sel_hi:[1,0]
	v_cmp_lt_i32_e32 vcc, s3, v44
	s_or_b64 s[0:1], vcc, s[0:1]
	s_waitcnt vmcnt(0)
	v_pk_fma_f32 v[0:1], v[0:1], v[52:53], v[4:5]
	v_pk_fma_f32 v[2:3], v[2:3], v[68:69], v[6:7]
	global_store_dwordx4 v[42:43], v[0:3], off offset:-3072
	global_load_dwordx4 v[0:3], v[16:17], off
	s_nop 0
	global_load_dwordx4 v[4:7], v[18:19], off
	v_pk_mul_f32 v[52:53], v[54:55], v[84:85] op_sel_hi:[1,0]
	v_pk_mul_f32 v[54:55], v[74:75], v[84:85] op_sel_hi:[1,0]
	s_waitcnt vmcnt(0)
	v_pk_fma_f32 v[0:1], v[0:1], v[52:53], v[4:5]
	v_pk_fma_f32 v[2:3], v[2:3], v[54:55], v[6:7]
	global_store_dwordx4 v[42:43], v[0:3], off offset:-2048
	global_load_dwordx4 v[0:3], v[20:21], off
	s_nop 0
	global_load_dwordx4 v[4:7], v[22:23], off
	v_pk_mul_f32 v[52:53], v[56:57], v[84:85] op_sel_hi:[1,0]
	v_pk_mul_f32 v[54:55], v[76:77], v[84:85] op_sel_hi:[1,0]
	s_waitcnt vmcnt(0)
	v_pk_fma_f32 v[0:1], v[52:53], v[0:1], v[4:5]
	v_pk_fma_f32 v[2:3], v[54:55], v[2:3], v[6:7]
	global_store_dwordx4 v[42:43], v[0:3], off offset:-1024
	global_load_dwordx4 v[0:3], v[24:25], off
	s_nop 0
	global_load_dwordx4 v[4:7], v[26:27], off
	v_pk_mul_f32 v[52:53], v[58:59], v[84:85] op_sel_hi:[1,0]
	v_pk_mul_f32 v[54:55], v[78:79], v[84:85] op_sel_hi:[1,0]
	s_waitcnt vmcnt(0)
	v_pk_fma_f32 v[0:1], v[52:53], v[0:1], v[4:5]
	v_pk_fma_f32 v[2:3], v[54:55], v[2:3], v[6:7]
	global_store_dwordx4 v[42:43], v[0:3], off
	global_load_dwordx4 v[0:3], v[28:29], off
	s_nop 0
	global_load_dwordx4 v[4:7], v[30:31], off
	v_pk_mul_f32 v[52:53], v[60:61], v[84:85] op_sel_hi:[1,0]
	v_pk_mul_f32 v[54:55], v[80:81], v[84:85] op_sel_hi:[1,0]
	s_waitcnt vmcnt(0)
	v_pk_fma_f32 v[0:1], v[52:53], v[0:1], v[4:5]
	v_pk_fma_f32 v[2:3], v[54:55], v[2:3], v[6:7]
	global_store_dwordx4 v[42:43], v[0:3], off offset:1024
	global_load_dwordx4 v[0:3], v[32:33], off
	s_nop 0
	global_load_dwordx4 v[4:7], v[34:35], off
	v_pk_mul_f32 v[52:53], v[62:63], v[84:85] op_sel_hi:[1,0]
	v_pk_mul_f32 v[54:55], v[82:83], v[84:85] op_sel_hi:[1,0]
	s_waitcnt vmcnt(0)
	v_pk_fma_f32 v[0:1], v[52:53], v[0:1], v[4:5]
	v_pk_fma_f32 v[2:3], v[54:55], v[2:3], v[6:7]
	global_store_dwordx4 v[42:43], v[0:3], off offset:2048
	global_load_dwordx4 v[0:3], v[36:37], off
	s_nop 0
	global_load_dwordx4 v[4:7], v[38:39], off
	v_pk_mul_f32 v[52:53], v[64:65], v[84:85] op_sel_hi:[1,0]
	v_pk_mul_f32 v[54:55], v[66:67], v[84:85] op_sel_hi:[1,0]
	s_waitcnt vmcnt(0)
	v_pk_fma_f32 v[0:1], v[52:53], v[0:1], v[4:5]
	v_pk_fma_f32 v[2:3], v[54:55], v[2:3], v[6:7]
	global_store_dwordx4 v[42:43], v[0:3], off offset:3072
	v_lshl_add_u64 v[42:43], v[42:43], 0, s[12:13]
	s_andn2_b64 exec, exec, s[0:1]
	s_cbranch_execnz .LBB0_1050
